# v28: v27 + GEMM main-loop heads aligned to 64 bytes
# speedup vs baseline: 1.0028x; 1.0028x over previous
; #define PG8_STAGE(bufoff, gbase, voff) do { _Pragma("unroll") for (int _i = 0; _i < 2; ++_i) \
;         __builtin_amdgcn_global_load_lds((const unsigned*)((const char*)(gbase) + (voff)[_i]), (LAS unsigned*)(lds + (bufoff) + ldsw + _i * 8192), 16, 0, 0); } while (0)
; #define PG8_LDA(dst, b, h) do { _Pragma("unroll") for (int m = 0; m < 4; ++m) _Pragma("unroll") for (int k = 0; k < 2; ++k) dst[m][k] = *(const LAS f16x8*)(lds + PG8_SA(b, h) + aoff + m * 2048 + k * 1024); } while (0)
; #define PG8_LDB(dst, b, h) do { _Pragma("unroll") for (int n = 0; n < 2; ++n) _Pragma("unroll") for (int k = 0; k < 2; ++k) dst[n][k] = *(const LAS f16x8*)(lds + PG8_SB(b, h) + boff + n * 2048 + k * 1024); } while (0)
; #define PG8_MMA(ai, bj, At, Bt) do { __builtin_amdgcn_s_setprio(1); _Pragma("unroll") for (int m = 0; m < 4; ++m) _Pragma("unroll") for (int n = 0; n < 2; ++n) _Pragma("unroll") for (int k = 0; k < 2; ++k) \
;         acc[ai][bj][m][n] = mma16_<Epi::BF16>(Bt[n][k], At[m][k], acc[ai][bj][m][n]); __builtin_amdgcn_s_setprio(0); } while (0)
; #define PG8_WAIT_V(n) asm volatile("s_waitcnt vmcnt(" #n ")" ::: "memory")
; #define PG8_WAIT_L(n) asm volatile("s_waitcnt lgkmcnt(" #n ")" ::: "memory")
;     ...
;         const bool has_next = S.next(ui + 1, nxt);
;         const char* nA = has_next ? (const char*)g.A + (size_t)nxt.pm * tA + (nxt.roff ? hA : (size_t)0) : cA; const char* nB = has_next ? (const char*)g.Bt + (size_t)nxt.pn * tB : cB;
;         for (int t = 0; t < nt; t += 2) {
;             const bool last = (t == nt - 2);
;             const char* a1 = cA + (size_t)(t + 1) * kstep;
;             const char* a2 = last ? nA : cA + (size_t)(t + 2) * kstep; const char* b2 = last ? nB : cB + (size_t)(t + 2) * kstep;
;             const char* a3 = a2 + kstep; const char* b3 = b2 + kstep;
;             if constexpr (SP2) {
;             PG8_LDB(B0, 0, 0); PG8_LDB(B1, 0, 1); PG8_SCHED; PG8_LDA(At, 0, 0); PG8_STAGE(PG8_SA(1, 1), a1 + hA, voffA);
;             PG8_WAIT_V(8); PG8_WAIT_L(0); PG8_BAR; PG8_MMA(0, 0, At, B0); PG8_MMA(0, 1, At, B1); PG8_BAR; PG8_SCHED;
;             PG8_LDA(At, 0, 1); PG8_STAGE(PG8_SB(0, 0), b2, voffB); PG8_STAGE(PG8_SB(0, 1), b2 + hB, voffB); PG8_STAGE(PG8_SA(0, 0), a2, voffA);
;             PG8_WAIT_V(8); PG8_WAIT_L(0); PG8_BAR; if (!cur.half) { PG8_MMA(1, 0, At, B0); PG8_MMA(1, 1, At, B1); } PG8_BAR; PG8_SCHED;
.LBB0_156:
	s_ashr_i32 s19, s18, 31
	s_lshl_b64 s[2:3], s[18:19], 19
	s_add_u32 s20, s13, s2
	s_addc_u32 s21, s14, s3
	s_and_b64 s[2:3], s[38:39], exec
	s_cselect_b32 s2, s21, s27
	s_cselect_b32 s3, s20, s26
	s_ashr_i32 s11, s10, 31
	s_lshl_b64 s[22:23], s[10:11], 19
	s_add_u32 s22, s1, s22
	s_addc_u32 s23, s12, s23
	s_and_b64 s[30:31], s[38:39], exec
	s_cselect_b32 s11, s23, s29
	s_cselect_b32 s19, s22, s28
	s_add_u32 s26, s26, 0x40080
	s_addc_u32 s27, s27, 0
	s_add_u32 s47, s28, 0x100
	s_addc_u32 s48, s29, 0
	s_mov_b32 s49, -2
	s_add_u32 s28, s26, 0xfffc0080
	s_addc_u32 s29, s27, -1
	s_add_i32 s50, 0, 0x10000
	s_cmp_eq_u32 s49, 12
	s_cselect_b32 s31, s2, s29
	s_cselect_b32 s30, s3, s28
	s_cselect_b32 s29, s11, s48
	s_cselect_b32 s28, s19, s47
	s_add_i32 s52, 0, 0x14000
	v_add_u32_e32 v156, s50, v141
	v_add_u32_e32 v172, s52, v141
	ds_read_b128 v[144:147], v156
	ds_read_b128 v[148:151], v156 offset:1024
	ds_read_b128 v[152:155], v156 offset:2048
	ds_read_b128 v[156:159], v156 offset:3072
	ds_read_b128 v[160:163], v172
	ds_read_b128 v[164:167], v172 offset:1024
	ds_read_b128 v[168:171], v172 offset:2048
	ds_read_b128 v[172:175], v172 offset:3072
	s_add_i32 m0, s25, 0xc000
	ds_read_b128 v[176:179], v143
	ds_read_b128 v[180:183], v143 offset:1024
	ds_read_b128 v[184:187], v143 offset:2048
	ds_read_b128 v[188:191], v143 offset:3072
	ds_read_b128 v[192:195], v143 offset:4096
	ds_read_b128 v[214:217], v143 offset:5120
	ds_read_b128 v[218:221], v143 offset:6144
	ds_read_b128 v[222:225], v143 offset:7168
	global_load_lds_dwordx4 v136, s[26:27]
	s_add_i32 m0, s25, 0xe000
	s_nop 0
	global_load_lds_dwordx4 v138, s[26:27]
	s_waitcnt vmcnt(8) lgkmcnt(0)
	s_barrier
	s_setprio 1
	v_mfma_f32_16x16x32_bf16 v[126:129], v[144:147], v[176:179], 0
	v_mfma_f32_16x16x32_bf16 v[118:121], v[152:155], v[176:179], 0
	v_mfma_f32_16x16x32_bf16 v[110:113], v[144:147], v[184:187], 0
	v_mfma_f32_16x16x32_bf16 v[102:105], v[152:155], v[184:187], 0
	v_mfma_f32_16x16x32_bf16 v[94:97], v[144:147], v[192:195], 0
	v_mfma_f32_16x16x32_bf16 v[86:89], v[152:155], v[192:195], 0
	v_mfma_f32_16x16x32_bf16 v[78:81], v[144:147], v[218:221], 0
	v_mfma_f32_16x16x32_bf16 v[70:73], v[152:155], v[218:221], 0
	v_mfma_f32_16x16x32_bf16 v[126:129], v[148:151], v[180:183], v[126:129]
	v_mfma_f32_16x16x32_bf16 v[118:121], v[156:159], v[180:183], v[118:121]
	v_mfma_f32_16x16x32_bf16 v[110:113], v[148:151], v[188:191], v[110:113]
	v_mfma_f32_16x16x32_bf16 v[102:105], v[156:159], v[188:191], v[102:105]
	v_mfma_f32_16x16x32_bf16 v[94:97], v[148:151], v[214:217], v[94:97]
	v_mfma_f32_16x16x32_bf16 v[86:89], v[156:159], v[214:217], v[86:89]
	v_mfma_f32_16x16x32_bf16 v[78:81], v[148:151], v[222:225], v[78:81]
	v_mfma_f32_16x16x32_bf16 v[70:73], v[156:159], v[222:225], v[70:73]
	s_setprio 0
	s_setprio 1
	v_mfma_f32_16x16x32_bf16 v[122:125], v[160:163], v[176:179], 0
	v_mfma_f32_16x16x32_bf16 v[114:117], v[168:171], v[176:179], 0
	v_mfma_f32_16x16x32_bf16 v[106:109], v[160:163], v[184:187], 0
	v_mfma_f32_16x16x32_bf16 v[98:101], v[168:171], v[184:187], 0
	v_mfma_f32_16x16x32_bf16 v[90:93], v[160:163], v[192:195], 0
	v_mfma_f32_16x16x32_bf16 v[82:85], v[168:171], v[192:195], 0
	v_mfma_f32_16x16x32_bf16 v[74:77], v[160:163], v[218:221], 0
	v_mfma_f32_16x16x32_bf16 v[66:69], v[168:171], v[218:221], 0
	v_mfma_f32_16x16x32_bf16 v[122:125], v[164:167], v[180:183], v[122:125]
	v_mfma_f32_16x16x32_bf16 v[114:117], v[172:175], v[180:183], v[114:117]
	v_mfma_f32_16x16x32_bf16 v[106:109], v[164:167], v[188:191], v[106:109]
	v_mfma_f32_16x16x32_bf16 v[98:101], v[172:175], v[188:191], v[98:101]
	v_mfma_f32_16x16x32_bf16 v[90:93], v[164:167], v[214:217], v[90:93]
	v_mfma_f32_16x16x32_bf16 v[82:85], v[172:175], v[214:217], v[82:85]
	v_mfma_f32_16x16x32_bf16 v[74:77], v[164:167], v[222:225], v[74:77]
	v_mfma_f32_16x16x32_bf16 v[66:69], v[172:175], v[222:225], v[66:69]
	s_setprio 0
	s_barrier
	s_add_i32 s50, s50, s34
	s_mov_b32 m0, s50
	ds_read_b128 v[176:179], v143 offset:16384
	ds_read_b128 v[180:183], v143 offset:17408
	ds_read_b128 v[184:187], v143 offset:18432
	ds_read_b128 v[188:191], v143 offset:19456
	ds_read_b128 v[192:195], v143 offset:20480
	ds_read_b128 v[214:217], v143 offset:21504
	ds_read_b128 v[218:221], v143 offset:22528
	ds_read_b128 v[222:225], v143 offset:23552
	global_load_lds_dwordx4 v0, s[28:29]
	s_add_i32 m0, s50, 0x2000
	s_add_u32 s50, s28, 0x40000
	s_addc_u32 s51, s29, 0
	s_add_i32 s52, s52, s34
	global_load_lds_dwordx4 v130, s[28:29]
	s_mov_b32 m0, s52
	s_nop 0
	global_load_lds_dwordx4 v0, s[50:51]
	s_add_i32 m0, s52, 0x2000
	s_nop 0
	global_load_lds_dwordx4 v130, s[50:51]
	s_mov_b32 m0, s25
	s_nop 0
	global_load_lds_dwordx4 v134, s[30:31]
	s_mov_b32 m0, s36
	s_nop 0
	global_load_lds_dwordx4 v132, s[30:31]
	s_waitcnt vmcnt(8) lgkmcnt(0)
	s_barrier
; #define PG8_STAGE(bufoff, gbase, voff) do { _Pragma("unroll") for (int _i = 0; _i < 2; ++_i) \
;         __builtin_amdgcn_global_load_lds((const unsigned*)((const char*)(gbase) + (voff)[_i]), (LAS unsigned*)(lds + (bufoff) + ldsw + _i * 8192), 16, 0, 0); } while (0)
; #define PG8_LDA(dst, b, h) do { _Pragma("unroll") for (int m = 0; m < 4; ++m) _Pragma("unroll") for (int k = 0; k < 2; ++k) dst[m][k] = *(const LAS f16x8*)(lds + PG8_SA(b, h) + aoff + m * 2048 + k * 1024); } while (0)
; #define PG8_LDB(dst, b, h) do { _Pragma("unroll") for (int n = 0; n < 2; ++n) _Pragma("unroll") for (int k = 0; k < 2; ++k) dst[n][k] = *(const LAS f16x8*)(lds + PG8_SB(b, h) + boff + n * 2048 + k * 1024); } while (0)
; #define PG8_MMA(ai, bj, At, Bt) do { __builtin_amdgcn_s_setprio(1); _Pragma("unroll") for (int m = 0; m < 4; ++m) _Pragma("unroll") for (int n = 0; n < 2; ++n) _Pragma("unroll") for (int k = 0; k < 2; ++k) \
;         acc[ai][bj][m][n] = mma16_<Epi::BF16>(Bt[n][k], At[m][k], acc[ai][bj][m][n]); __builtin_amdgcn_s_setprio(0); } while (0)
; #define PG8_WAIT_V(n) asm volatile("s_waitcnt vmcnt(" #n ")" ::: "memory")
; #define PG8_WAIT_L(n) asm volatile("s_waitcnt lgkmcnt(" #n ")" ::: "memory")
; #define PG8_BAR __builtin_amdgcn_s_barrier()
; #define PG8_SCHED __builtin_amdgcn_sched_barrier(0)
;     ...
;             PG8_WAIT_V(8); PG8_WAIT_L(0); PG8_BAR; if (!cur.half) { PG8_MMA(1, 0, At, B0); PG8_MMA(1, 1, At, B1); } PG8_BAR; PG8_SCHED;
;             PG8_LDB(B0, 1, 0); PG8_LDB(B1, 1, 1); PG8_SCHED; PG8_LDA(At, 1, 0); PG8_STAGE(PG8_SA(0, 1), a2 + hA, voffA);
;             PG8_WAIT_V(8); PG8_WAIT_L(0); PG8_BAR; PG8_MMA(0, 0, At, B0); PG8_MMA(0, 1, At, B1); PG8_BAR; PG8_SCHED;
	s_setprio 1
	v_mfma_f32_16x16x32_bf16 v[62:65], v[144:147], v[176:179], 0
	v_mfma_f32_16x16x32_bf16 v[54:57], v[152:155], v[176:179], 0
	v_mfma_f32_16x16x32_bf16 v[46:49], v[144:147], v[184:187], 0
	v_mfma_f32_16x16x32_bf16 v[38:41], v[152:155], v[184:187], 0
	v_mfma_f32_16x16x32_bf16 v[30:33], v[144:147], v[192:195], 0
	v_mfma_f32_16x16x32_bf16 v[22:25], v[152:155], v[192:195], 0
	v_mfma_f32_16x16x32_bf16 v[14:17], v[144:147], v[218:221], 0
	v_mfma_f32_16x16x32_bf16 v[6:9], v[152:155], v[218:221], 0
	v_mfma_f32_16x16x32_bf16 v[62:65], v[148:151], v[180:183], v[62:65]
	v_mfma_f32_16x16x32_bf16 v[54:57], v[156:159], v[180:183], v[54:57]
	v_mfma_f32_16x16x32_bf16 v[46:49], v[148:151], v[188:191], v[46:49]
	v_mfma_f32_16x16x32_bf16 v[38:41], v[156:159], v[188:191], v[38:41]
	v_mfma_f32_16x16x32_bf16 v[30:33], v[148:151], v[214:217], v[30:33]
	v_mfma_f32_16x16x32_bf16 v[22:25], v[156:159], v[214:217], v[22:25]
	v_mfma_f32_16x16x32_bf16 v[14:17], v[148:151], v[222:225], v[14:17]
	v_mfma_f32_16x16x32_bf16 v[6:9], v[156:159], v[222:225], v[6:9]
	s_setprio 0
	s_setprio 1
	v_mfma_f32_16x16x32_bf16 v[58:61], v[160:163], v[176:179], 0
	v_mfma_f32_16x16x32_bf16 v[50:53], v[168:171], v[176:179], 0
	v_mfma_f32_16x16x32_bf16 v[42:45], v[160:163], v[184:187], 0
	v_mfma_f32_16x16x32_bf16 v[34:37], v[168:171], v[184:187], 0
	v_mfma_f32_16x16x32_bf16 v[26:29], v[160:163], v[192:195], 0
	v_mfma_f32_16x16x32_bf16 v[18:21], v[168:171], v[192:195], 0
	v_mfma_f32_16x16x32_bf16 v[10:13], v[160:163], v[218:221], 0
	v_mfma_f32_16x16x32_bf16 v[2:5], v[168:171], v[218:221], 0
	v_mfma_f32_16x16x32_bf16 v[58:61], v[164:167], v[180:183], v[58:61]
	v_mfma_f32_16x16x32_bf16 v[50:53], v[172:175], v[180:183], v[50:53]
	v_mfma_f32_16x16x32_bf16 v[42:45], v[164:167], v[188:191], v[42:45]
	v_mfma_f32_16x16x32_bf16 v[34:37], v[172:175], v[188:191], v[34:37]
	v_mfma_f32_16x16x32_bf16 v[26:29], v[164:167], v[214:217], v[26:29]
	v_mfma_f32_16x16x32_bf16 v[18:21], v[172:175], v[214:217], v[18:21]
	v_mfma_f32_16x16x32_bf16 v[10:13], v[164:167], v[222:225], v[10:13]
	v_mfma_f32_16x16x32_bf16 v[2:5], v[172:175], v[222:225], v[2:5]
	s_setprio 0
	s_barrier
	s_add_i32 s50, 0, 0x18000
	s_add_i32 s51, 0, 0x1c000
	v_add_u32_e32 v156, s50, v141
	v_add_u32_e32 v172, s51, v141
	ds_read_b128 v[144:147], v156
	ds_read_b128 v[148:151], v156 offset:1024
	ds_read_b128 v[152:155], v156 offset:2048
	ds_read_b128 v[156:159], v156 offset:3072
	ds_read_b128 v[160:163], v172
	ds_read_b128 v[164:167], v172 offset:1024
	ds_read_b128 v[168:171], v172 offset:2048
	ds_read_b128 v[172:175], v172 offset:3072
	s_add_u32 s30, s30, 0x40000
	s_addc_u32 s31, s31, 0
	s_add_u32 s98, s30, 0xfffc0080
	s_addc_u32 s99, s31, -1
	s_mov_b32 m0, s37
	ds_read_b128 v[176:179], v143 offset:32768
	ds_read_b128 v[180:183], v143 offset:33792
	ds_read_b128 v[184:187], v143 offset:34816
	ds_read_b128 v[188:191], v143 offset:35840
	ds_read_b128 v[192:195], v143 offset:36864
	ds_read_b128 v[214:217], v143 offset:37888
	ds_read_b128 v[218:221], v143 offset:38912
	ds_read_b128 v[222:225], v143 offset:39936
	global_load_lds_dwordx4 v134, s[30:31]
	s_mov_b32 m0, s40
	s_nop 0
	global_load_lds_dwordx4 v132, s[30:31]
	s_waitcnt vmcnt(8) lgkmcnt(0)
	s_barrier
	s_setprio 1
	v_mfma_f32_16x16x32_bf16 v[126:129], v[144:147], v[176:179], v[126:129]
	v_mfma_f32_16x16x32_bf16 v[118:121], v[152:155], v[176:179], v[118:121]
	v_mfma_f32_16x16x32_bf16 v[110:113], v[144:147], v[184:187], v[110:113]
	v_mfma_f32_16x16x32_bf16 v[102:105], v[152:155], v[184:187], v[102:105]
	v_mfma_f32_16x16x32_bf16 v[94:97], v[144:147], v[192:195], v[94:97]
	v_mfma_f32_16x16x32_bf16 v[86:89], v[152:155], v[192:195], v[86:89]
	v_mfma_f32_16x16x32_bf16 v[78:81], v[144:147], v[218:221], v[78:81]
	v_mfma_f32_16x16x32_bf16 v[70:73], v[152:155], v[218:221], v[70:73]
	v_mfma_f32_16x16x32_bf16 v[126:129], v[148:151], v[180:183], v[126:129]
	v_mfma_f32_16x16x32_bf16 v[118:121], v[156:159], v[180:183], v[118:121]
	v_mfma_f32_16x16x32_bf16 v[110:113], v[148:151], v[188:191], v[110:113]
	v_mfma_f32_16x16x32_bf16 v[102:105], v[156:159], v[188:191], v[102:105]
	v_mfma_f32_16x16x32_bf16 v[94:97], v[148:151], v[214:217], v[94:97]
	v_mfma_f32_16x16x32_bf16 v[86:89], v[156:159], v[214:217], v[86:89]
	v_mfma_f32_16x16x32_bf16 v[78:81], v[148:151], v[222:225], v[78:81]
	v_mfma_f32_16x16x32_bf16 v[70:73], v[156:159], v[222:225], v[70:73]
	s_setprio 0
	s_setprio 1
	v_mfma_f32_16x16x32_bf16 v[122:125], v[160:163], v[176:179], v[122:125]
	v_mfma_f32_16x16x32_bf16 v[114:117], v[168:171], v[176:179], v[114:117]
	v_mfma_f32_16x16x32_bf16 v[106:109], v[160:163], v[184:187], v[106:109]
	v_mfma_f32_16x16x32_bf16 v[98:101], v[168:171], v[184:187], v[98:101]
	v_mfma_f32_16x16x32_bf16 v[90:93], v[160:163], v[192:195], v[90:93]
	v_mfma_f32_16x16x32_bf16 v[82:85], v[168:171], v[192:195], v[82:85]
	v_mfma_f32_16x16x32_bf16 v[74:77], v[160:163], v[218:221], v[74:77]
	v_mfma_f32_16x16x32_bf16 v[66:69], v[168:171], v[218:221], v[66:69]
	v_mfma_f32_16x16x32_bf16 v[122:125], v[164:167], v[180:183], v[122:125]
	v_mfma_f32_16x16x32_bf16 v[114:117], v[172:175], v[180:183], v[114:117]
	v_mfma_f32_16x16x32_bf16 v[106:109], v[164:167], v[188:191], v[106:109]
	v_mfma_f32_16x16x32_bf16 v[98:101], v[172:175], v[188:191], v[98:101]
	v_mfma_f32_16x16x32_bf16 v[90:93], v[164:167], v[214:217], v[90:93]
	v_mfma_f32_16x16x32_bf16 v[82:85], v[172:175], v[214:217], v[82:85]
	v_mfma_f32_16x16x32_bf16 v[74:77], v[164:167], v[222:225], v[74:77]
	v_mfma_f32_16x16x32_bf16 v[66:69], v[172:175], v[222:225], v[66:69]
	s_setprio 0
	s_barrier
; #define PG8_STAGE(bufoff, gbase, voff) do { _Pragma("unroll") for (int _i = 0; _i < 2; ++_i) \
;         __builtin_amdgcn_global_load_lds((const unsigned*)((const char*)(gbase) + (voff)[_i]), (LAS unsigned*)(lds + (bufoff) + ldsw + _i * 8192), 16, 0, 0); } while (0)
; #define PG8_LDA(dst, b, h) do { _Pragma("unroll") for (int m = 0; m < 4; ++m) _Pragma("unroll") for (int k = 0; k < 2; ++k) dst[m][k] = *(const LAS f16x8*)(lds + PG8_SA(b, h) + aoff + m * 2048 + k * 1024); } while (0)
; #define PG8_MMA(ai, bj, At, Bt) do { __builtin_amdgcn_s_setprio(1); _Pragma("unroll") for (int m = 0; m < 4; ++m) _Pragma("unroll") for (int n = 0; n < 2; ++n) _Pragma("unroll") for (int k = 0; k < 2; ++k) \
;         acc[ai][bj][m][n] = mma16_<Epi::BF16>(Bt[n][k], At[m][k], acc[ai][bj][m][n]); __builtin_amdgcn_s_setprio(0); } while (0)
; #define PG8_WAIT_V(n) asm volatile("s_waitcnt vmcnt(" #n ")" ::: "memory")
; #define PG8_WAIT_L(n) asm volatile("s_waitcnt lgkmcnt(" #n ")" ::: "memory")
; #define PG8_BAR __builtin_amdgcn_s_barrier()
; #define PG8_SCHED __builtin_amdgcn_sched_barrier(0)
;     ...
;             PG8_LDA(At, 1, 1); PG8_STAGE(PG8_SB(1, 0), b3, voffB); PG8_STAGE(PG8_SB(1, 1), b3 + hB, voffB); PG8_STAGE(PG8_SA(1, 0), a3, voffA);
;             PG8_WAIT_V(8); PG8_WAIT_L(0); PG8_BAR; if (!cur.half) { PG8_MMA(1, 0, At, B0); PG8_MMA(1, 1, At, B1); } PG8_BAR; PG8_SCHED;
	s_add_i32 s30, s50, s34
	s_add_u32 s28, s28, 0x80
	s_addc_u32 s29, s29, 0
	s_mov_b32 m0, s30
	ds_read_b128 v[176:179], v143 offset:49152
	ds_read_b128 v[180:183], v143 offset:50176
	ds_read_b128 v[184:187], v143 offset:51200
	ds_read_b128 v[188:191], v143 offset:52224
	ds_read_b128 v[192:195], v143 offset:53248
	ds_read_b128 v[214:217], v143 offset:54272
	ds_read_b128 v[218:221], v143 offset:55296
	ds_read_b128 v[222:225], v143 offset:56320
	global_load_lds_dwordx4 v0, s[28:29]
	s_add_i32 m0, s30, 0x2000
	s_add_i32 s30, s51, s34
	global_load_lds_dwordx4 v130, s[28:29]
	s_add_u32 s28, s28, 0x40000
	s_addc_u32 s29, s29, 0
	s_mov_b32 m0, s30
	s_nop 0
	global_load_lds_dwordx4 v0, s[28:29]
	s_add_i32 m0, s30, 0x2000
	s_nop 0
	global_load_lds_dwordx4 v130, s[28:29]
	s_mov_b32 m0, s41
	s_nop 0
	global_load_lds_dwordx4 v134, s[98:99]
	s_mov_b32 m0, s42
	s_nop 0
	global_load_lds_dwordx4 v132, s[98:99]
	s_waitcnt vmcnt(8) lgkmcnt(0)
	s_barrier
	s_setprio 1
	v_mfma_f32_16x16x32_bf16 v[62:65], v[144:147], v[176:179], v[62:65]
	v_mfma_f32_16x16x32_bf16 v[54:57], v[152:155], v[176:179], v[54:57]
	v_mfma_f32_16x16x32_bf16 v[46:49], v[144:147], v[184:187], v[46:49]
	v_mfma_f32_16x16x32_bf16 v[38:41], v[152:155], v[184:187], v[38:41]
	v_mfma_f32_16x16x32_bf16 v[30:33], v[144:147], v[192:195], v[30:33]
	v_mfma_f32_16x16x32_bf16 v[22:25], v[152:155], v[192:195], v[22:25]
	v_mfma_f32_16x16x32_bf16 v[14:17], v[144:147], v[218:221], v[14:17]
	v_mfma_f32_16x16x32_bf16 v[6:9], v[152:155], v[218:221], v[6:9]
	v_mfma_f32_16x16x32_bf16 v[62:65], v[148:151], v[180:183], v[62:65]
	v_mfma_f32_16x16x32_bf16 v[54:57], v[156:159], v[180:183], v[54:57]
	v_mfma_f32_16x16x32_bf16 v[46:49], v[148:151], v[188:191], v[46:49]
	v_mfma_f32_16x16x32_bf16 v[38:41], v[156:159], v[188:191], v[38:41]
	v_mfma_f32_16x16x32_bf16 v[30:33], v[148:151], v[214:217], v[30:33]
	v_mfma_f32_16x16x32_bf16 v[22:25], v[156:159], v[214:217], v[22:25]
	v_mfma_f32_16x16x32_bf16 v[14:17], v[148:151], v[222:225], v[14:17]
	v_mfma_f32_16x16x32_bf16 v[6:9], v[156:159], v[222:225], v[6:9]
	s_setprio 0
	s_setprio 1
	v_mfma_f32_16x16x32_bf16 v[58:61], v[160:163], v[176:179], v[58:61]
	v_mfma_f32_16x16x32_bf16 v[50:53], v[168:171], v[176:179], v[50:53]
	v_mfma_f32_16x16x32_bf16 v[42:45], v[160:163], v[184:187], v[42:45]
	v_mfma_f32_16x16x32_bf16 v[34:37], v[168:171], v[184:187], v[34:37]
	v_mfma_f32_16x16x32_bf16 v[26:29], v[160:163], v[192:195], v[26:29]
	v_mfma_f32_16x16x32_bf16 v[18:21], v[168:171], v[192:195], v[18:21]
	v_mfma_f32_16x16x32_bf16 v[10:13], v[160:163], v[218:221], v[10:13]
	v_mfma_f32_16x16x32_bf16 v[2:5], v[168:171], v[218:221], v[2:5]
	v_mfma_f32_16x16x32_bf16 v[58:61], v[164:167], v[180:183], v[58:61]
	v_mfma_f32_16x16x32_bf16 v[50:53], v[172:175], v[180:183], v[50:53]
	v_mfma_f32_16x16x32_bf16 v[42:45], v[164:167], v[188:191], v[42:45]
	v_mfma_f32_16x16x32_bf16 v[34:37], v[172:175], v[188:191], v[34:37]
	v_mfma_f32_16x16x32_bf16 v[26:29], v[164:167], v[214:217], v[26:29]
	v_mfma_f32_16x16x32_bf16 v[18:21], v[172:175], v[214:217], v[18:21]
	v_mfma_f32_16x16x32_bf16 v[10:13], v[164:167], v[222:225], v[10:13]
	v_mfma_f32_16x16x32_bf16 v[2:5], v[172:175], v[222:225], v[2:5]
	s_setprio 0
	s_barrier
	s_add_i32 s49, s49, 2
	s_add_u32 s26, s26, 0x100
	s_addc_u32 s27, s27, 0
	s_add_u32 s47, s47, 0x100
	s_addc_u32 s48, s48, 0
	s_cmp_gt_u32 s49, 13
	.p2align	6

; #define PG8_STAGE(bufoff, gbase, voff) do { _Pragma("unroll") for (int _i = 0; _i < 2; ++_i) \
;         __builtin_amdgcn_global_load_lds((const unsigned*)((const char*)(gbase) + (voff)[_i]), (LAS unsigned*)(lds + (bufoff) + ldsw + _i * 8192), 16, 0, 0); } while (0)
; #define PG8_LDA(dst, b, h) do { _Pragma("unroll") for (int m = 0; m < 4; ++m) _Pragma("unroll") for (int k = 0; k < 2; ++k) dst[m][k] = *(const LAS f16x8*)(lds + PG8_SA(b, h) + aoff + m * 2048 + k * 1024); } while (0)
; #define PG8_LDB(dst, b, h) do { _Pragma("unroll") for (int n = 0; n < 2; ++n) _Pragma("unroll") for (int k = 0; k < 2; ++k) dst[n][k] = *(const LAS f16x8*)(lds + PG8_SB(b, h) + boff + n * 2048 + k * 1024); } while (0)
; #define PG8_WAIT_V(n) asm volatile("s_waitcnt vmcnt(" #n ")" ::: "memory")
; #define PG8_WAIT_L(n) asm volatile("s_waitcnt lgkmcnt(" #n ")" ::: "memory")
; #define PG8_BAR __builtin_amdgcn_s_barrier()
;     ...
;         for (int t = 0; t < nt; t += 2) {
;             const bool last = (t == nt - 2);
;             const char* a1 = cA + (size_t)(t + 1) * kstep;
;             const char* a2 = last ? nA : cA + (size_t)(t + 2) * kstep; const char* b2 = last ? nB : cB + (size_t)(t + 2) * kstep;
;             const char* a3 = a2 + kstep; const char* b3 = b2 + kstep;
;             if constexpr (SP2) {
;             PG8_LDB(B0, 0, 0); PG8_LDB(B1, 0, 1); PG8_SCHED; PG8_LDA(At, 0, 0); PG8_STAGE(PG8_SA(1, 1), a1 + hA, voffA);
;             PG8_WAIT_V(8); PG8_WAIT_L(0); PG8_BAR; PG8_MMA(0, 0, At, B0); PG8_MMA(0, 1, At, B1); PG8_BAR; PG8_SCHED;
;             PG8_LDA(At, 0, 1); PG8_STAGE(PG8_SB(0, 0), b2, voffB); PG8_STAGE(PG8_SB(0, 1), b2 + hB, voffB); PG8_STAGE(PG8_SA(0, 0), a2, voffA);
;             PG8_WAIT_V(8); PG8_WAIT_L(0); PG8_BAR; if (!cur.half) { PG8_MMA(1, 0, At, B0); PG8_MMA(1, 1, At, B1); } PG8_BAR; PG8_SCHED;
;             PG8_LDB(B0, 1, 0); PG8_LDB(B1, 1, 1); PG8_SCHED; PG8_LDA(At, 1, 0); PG8_STAGE(PG8_SA(0, 1), a2 + hA, voffA);
;             PG8_WAIT_V(8); PG8_WAIT_L(0); PG8_BAR; PG8_MMA(0, 0, At, B0); PG8_MMA(0, 1, At, B1); PG8_BAR; PG8_SCHED;
;             PG8_LDA(At, 1, 1); PG8_STAGE(PG8_SB(1, 0), b3, voffB); PG8_STAGE(PG8_SB(1, 1), b3 + hB, voffB); PG8_STAGE(PG8_SA(1, 0), a3, voffA);
;             PG8_WAIT_V(8); PG8_WAIT_L(0); PG8_BAR; if (!cur.half) { PG8_MMA(1, 0, At, B0); PG8_MMA(1, 1, At, B1); } PG8_BAR; PG8_SCHED;
.LBB0_241:
	s_barrier
	s_add_i32 s14, s14, 2
	s_add_u32 s2, s2, 0x100
	s_addc_u32 s3, s3, 0
	s_cmp_gt_u32 s14, 41
	s_cbranch_scc1 .LBB0_246
	.p2align	6

; #define PG8_STAGE(bufoff, gbase, voff) do { _Pragma("unroll") for (int _i = 0; _i < 2; ++_i) \
;         __builtin_amdgcn_global_load_lds((const unsigned*)((const char*)(gbase) + (voff)[_i]), (LAS unsigned*)(lds + (bufoff) + ldsw + _i * 8192), 16, 0, 0); } while (0)
; #define PG8_LDA(dst, b, h) do { _Pragma("unroll") for (int m = 0; m < 4; ++m) _Pragma("unroll") for (int k = 0; k < 2; ++k) dst[m][k] = *(const LAS f16x8*)(lds + PG8_SA(b, h) + aoff + m * 2048 + k * 1024); } while (0)
; #define PG8_LDB(dst, b, h) do { _Pragma("unroll") for (int n = 0; n < 2; ++n) _Pragma("unroll") for (int k = 0; k < 2; ++k) dst[n][k] = *(const LAS f16x8*)(lds + PG8_SB(b, h) + boff + n * 2048 + k * 1024); } while (0)
; #define PG8_MMA(ai, bj, At, Bt) do { __builtin_amdgcn_s_setprio(1); _Pragma("unroll") for (int m = 0; m < 4; ++m) _Pragma("unroll") for (int n = 0; n < 2; ++n) _Pragma("unroll") for (int k = 0; k < 2; ++k) \
;         acc[ai][bj][m][n] = mma16_<Epi::BF16>(Bt[n][k], At[m][k], acc[ai][bj][m][n]); __builtin_amdgcn_s_setprio(0); } while (0)
; #define PG8_WAIT_V(n) asm volatile("s_waitcnt vmcnt(" #n ")" ::: "memory")
; #define PG8_WAIT_L(n) asm volatile("s_waitcnt lgkmcnt(" #n ")" ::: "memory")
; #define PG8_BAR __builtin_amdgcn_s_barrier()
;     ...
;         const char* nA = has_next ? (const char*)g.A + (size_t)nxt.pm * tA + (nxt.roff ? hA : (size_t)0) : cA; const char* nB = has_next ? (const char*)g.Bt + (size_t)nxt.pn * tB : cB;
;         for (int t = 0; t < nt; t += 2) {
;             const bool last = (t == nt - 2);
;             const char* a1 = cA + (size_t)(t + 1) * kstep;
;             const char* a2 = last ? nA : cA + (size_t)(t + 2) * kstep; const char* b2 = last ? nB : cB + (size_t)(t + 2) * kstep;
;             const char* a3 = a2 + kstep; const char* b3 = b2 + kstep;
;             if constexpr (SP2) {
;             PG8_LDB(B0, 0, 0); PG8_LDB(B1, 0, 1); PG8_SCHED; PG8_LDA(At, 0, 0); PG8_STAGE(PG8_SA(1, 1), a1 + hA, voffA);
;             PG8_WAIT_V(8); PG8_WAIT_L(0); PG8_BAR; PG8_MMA(0, 0, At, B0); PG8_MMA(0, 1, At, B1); PG8_BAR; PG8_SCHED;
;             PG8_LDA(At, 0, 1); PG8_STAGE(PG8_SB(0, 0), b2, voffB); PG8_STAGE(PG8_SB(0, 1), b2 + hB, voffB); PG8_STAGE(PG8_SA(0, 0), a2, voffA);
;             PG8_WAIT_V(8); PG8_WAIT_L(0); PG8_BAR; if (!cur.half) { PG8_MMA(1, 0, At, B0); PG8_MMA(1, 1, At, B1); } PG8_BAR; PG8_SCHED;
.LBB0_515:
	s_ashr_i32 s21, s20, 31
	s_lshl_b64 s[2:3], s[20:21], 19
	s_add_u32 s22, s13, s2
	s_addc_u32 s23, s14, s3
	s_and_b64 s[2:3], s[38:39], exec
	s_cselect_b32 s2, s23, s27
	s_cselect_b32 s3, s22, s26
	s_ashr_i32 s19, s18, 31
	s_lshl_b64 s[24:25], s[18:19], 19
	s_add_u32 s24, s1, s24
	s_addc_u32 s25, s12, s25
	s_and_b64 s[30:31], s[38:39], exec
	s_cselect_b32 s19, s25, s29
	s_cselect_b32 s21, s24, s28
	s_add_u32 s26, s26, 0x40080
	s_addc_u32 s27, s27, 0
	s_add_u32 s47, s28, 0x100
	s_addc_u32 s48, s29, 0
	s_mov_b32 s49, -2
	s_add_u32 s28, s26, 0xfffc0080
	s_addc_u32 s29, s27, -1
	s_add_i32 s50, 0, 0x10000
	s_cmp_eq_u32 s49, 12
	s_cselect_b32 s31, s2, s29
	s_cselect_b32 s30, s3, s28
	v_add_u32_e32 v142, s50, v145
	s_cselect_b32 s29, s19, s48
	s_cselect_b32 s28, s21, s47
	s_add_i32 s52, 0, 0x14000
	ds_read_b128 v[148:151], v142
	ds_read_b128 v[152:155], v142 offset:1024
	ds_read_b128 v[156:159], v142 offset:2048
	ds_read_b128 v[160:163], v142 offset:3072
	v_add_u32_e32 v142, s52, v145
	ds_read_b128 v[164:167], v142
	ds_read_b128 v[168:171], v142 offset:1024
	ds_read_b128 v[172:175], v142 offset:2048
	ds_read_b128 v[176:179], v142 offset:3072
	s_add_i32 m0, s17, 0xc000
	ds_read_b128 v[180:183], v147
	ds_read_b128 v[184:187], v147 offset:1024
	ds_read_b128 v[188:191], v147 offset:2048
	ds_read_b128 v[192:195], v147 offset:3072
	ds_read_b128 v[214:217], v147 offset:4096
	ds_read_b128 v[218:221], v147 offset:5120
	ds_read_b128 v[222:225], v147 offset:6144
	ds_read_b128 v[226:229], v147 offset:7168
	global_load_lds_dwordx4 v138, s[26:27]
	s_add_i32 m0, s17, 0xe000
	s_nop 0
	global_load_lds_dwordx4 v140, s[26:27]
	s_waitcnt vmcnt(8) lgkmcnt(0)
	s_barrier
	s_setprio 1
	v_mfma_f32_16x16x32_bf16 v[126:129], v[148:151], v[180:183], 0
	v_mfma_f32_16x16x32_bf16 v[122:125], v[156:159], v[180:183], 0
	v_mfma_f32_16x16x32_bf16 v[118:121], v[148:151], v[188:191], 0
	v_mfma_f32_16x16x32_bf16 v[114:117], v[156:159], v[188:191], 0
	v_mfma_f32_16x16x32_bf16 v[102:105], v[148:151], v[214:217], 0
	v_mfma_f32_16x16x32_bf16 v[98:101], v[156:159], v[214:217], 0
	v_mfma_f32_16x16x32_bf16 v[86:89], v[148:151], v[222:225], 0
	v_mfma_f32_16x16x32_bf16 v[82:85], v[156:159], v[222:225], 0
	v_mfma_f32_16x16x32_bf16 v[126:129], v[152:155], v[184:187], v[126:129]
	v_mfma_f32_16x16x32_bf16 v[122:125], v[160:163], v[184:187], v[122:125]
	v_mfma_f32_16x16x32_bf16 v[118:121], v[152:155], v[192:195], v[118:121]
	v_mfma_f32_16x16x32_bf16 v[114:117], v[160:163], v[192:195], v[114:117]
	v_mfma_f32_16x16x32_bf16 v[102:105], v[152:155], v[218:221], v[102:105]
	v_mfma_f32_16x16x32_bf16 v[98:101], v[160:163], v[218:221], v[98:101]
	v_mfma_f32_16x16x32_bf16 v[86:89], v[152:155], v[226:229], v[86:89]
	v_mfma_f32_16x16x32_bf16 v[82:85], v[160:163], v[226:229], v[82:85]
	s_setprio 0
	s_setprio 1
	v_mfma_f32_16x16x32_bf16 v[110:113], v[164:167], v[180:183], 0
	v_mfma_f32_16x16x32_bf16 v[106:109], v[172:175], v[180:183], 0
	v_mfma_f32_16x16x32_bf16 v[94:97], v[164:167], v[188:191], 0
	v_mfma_f32_16x16x32_bf16 v[90:93], v[172:175], v[188:191], 0
	v_mfma_f32_16x16x32_bf16 v[78:81], v[164:167], v[214:217], 0
	v_mfma_f32_16x16x32_bf16 v[74:77], v[172:175], v[214:217], 0
	v_mfma_f32_16x16x32_bf16 v[70:73], v[164:167], v[222:225], 0
	v_mfma_f32_16x16x32_bf16 v[66:69], v[172:175], v[222:225], 0
	v_mfma_f32_16x16x32_bf16 v[110:113], v[168:171], v[184:187], v[110:113]
	v_mfma_f32_16x16x32_bf16 v[106:109], v[176:179], v[184:187], v[106:109]
	v_mfma_f32_16x16x32_bf16 v[94:97], v[168:171], v[192:195], v[94:97]
	v_mfma_f32_16x16x32_bf16 v[90:93], v[176:179], v[192:195], v[90:93]
	v_mfma_f32_16x16x32_bf16 v[78:81], v[168:171], v[218:221], v[78:81]
	v_mfma_f32_16x16x32_bf16 v[74:77], v[176:179], v[218:221], v[74:77]
	v_mfma_f32_16x16x32_bf16 v[70:73], v[168:171], v[226:229], v[70:73]
	v_mfma_f32_16x16x32_bf16 v[66:69], v[176:179], v[226:229], v[66:69]
	s_setprio 0
	s_barrier
	s_add_i32 s50, s50, s34
	s_mov_b32 m0, s50
	ds_read_b128 v[180:183], v147 offset:16384
	ds_read_b128 v[184:187], v147 offset:17408
	ds_read_b128 v[188:191], v147 offset:18432
	ds_read_b128 v[192:195], v147 offset:19456
	ds_read_b128 v[214:217], v147 offset:20480
	ds_read_b128 v[218:221], v147 offset:21504
	ds_read_b128 v[222:225], v147 offset:22528
	ds_read_b128 v[226:229], v147 offset:23552
	global_load_lds_dwordx4 v0, s[28:29]
	s_add_i32 m0, s50, 0x2000
	s_add_u32 s50, s28, 0x40000
	s_addc_u32 s51, s29, 0
	s_add_i32 s52, s52, s34
	global_load_lds_dwordx4 v130, s[28:29]
	s_mov_b32 m0, s52
	s_nop 0
	global_load_lds_dwordx4 v0, s[50:51]
	s_add_i32 m0, s52, 0x2000
	s_nop 0
	global_load_lds_dwordx4 v130, s[50:51]
	s_mov_b32 m0, s17
	s_nop 0
	global_load_lds_dwordx4 v134, s[30:31]
	s_mov_b32 m0, s36
	s_nop 0
	global_load_lds_dwordx4 v132, s[30:31]
	s_waitcnt vmcnt(8) lgkmcnt(0)
	s_barrier
; #define PG8_STAGE(bufoff, gbase, voff) do { _Pragma("unroll") for (int _i = 0; _i < 2; ++_i) \
;         __builtin_amdgcn_global_load_lds((const unsigned*)((const char*)(gbase) + (voff)[_i]), (LAS unsigned*)(lds + (bufoff) + ldsw + _i * 8192), 16, 0, 0); } while (0)
; #define PG8_LDA(dst, b, h) do { _Pragma("unroll") for (int m = 0; m < 4; ++m) _Pragma("unroll") for (int k = 0; k < 2; ++k) dst[m][k] = *(const LAS f16x8*)(lds + PG8_SA(b, h) + aoff + m * 2048 + k * 1024); } while (0)
; #define PG8_LDB(dst, b, h) do { _Pragma("unroll") for (int n = 0; n < 2; ++n) _Pragma("unroll") for (int k = 0; k < 2; ++k) dst[n][k] = *(const LAS f16x8*)(lds + PG8_SB(b, h) + boff + n * 2048 + k * 1024); } while (0)
; #define PG8_MMA(ai, bj, At, Bt) do { __builtin_amdgcn_s_setprio(1); _Pragma("unroll") for (int m = 0; m < 4; ++m) _Pragma("unroll") for (int n = 0; n < 2; ++n) _Pragma("unroll") for (int k = 0; k < 2; ++k) \
;         acc[ai][bj][m][n] = mma16_<Epi::BF16>(Bt[n][k], At[m][k], acc[ai][bj][m][n]); __builtin_amdgcn_s_setprio(0); } while (0)
; #define PG8_WAIT_V(n) asm volatile("s_waitcnt vmcnt(" #n ")" ::: "memory")
; #define PG8_WAIT_L(n) asm volatile("s_waitcnt lgkmcnt(" #n ")" ::: "memory")
; #define PG8_BAR __builtin_amdgcn_s_barrier()
; #define PG8_SCHED __builtin_amdgcn_sched_barrier(0)
;     ...
;             PG8_WAIT_V(8); PG8_WAIT_L(0); PG8_BAR; if (!cur.half) { PG8_MMA(1, 0, At, B0); PG8_MMA(1, 1, At, B1); } PG8_BAR; PG8_SCHED;
;             PG8_LDB(B0, 1, 0); PG8_LDB(B1, 1, 1); PG8_SCHED; PG8_LDA(At, 1, 0); PG8_STAGE(PG8_SA(0, 1), a2 + hA, voffA);
;             PG8_WAIT_V(8); PG8_WAIT_L(0); PG8_BAR; PG8_MMA(0, 0, At, B0); PG8_MMA(0, 1, At, B1); PG8_BAR; PG8_SCHED;
	s_setprio 1
	v_mfma_f32_16x16x32_bf16 v[62:65], v[148:151], v[180:183], 0
	v_mfma_f32_16x16x32_bf16 v[58:61], v[156:159], v[180:183], 0
	v_mfma_f32_16x16x32_bf16 v[54:57], v[148:151], v[188:191], 0
	v_mfma_f32_16x16x32_bf16 v[50:53], v[156:159], v[188:191], 0
	v_mfma_f32_16x16x32_bf16 v[38:41], v[148:151], v[214:217], 0
	v_mfma_f32_16x16x32_bf16 v[34:37], v[156:159], v[214:217], 0
	v_mfma_f32_16x16x32_bf16 v[22:25], v[148:151], v[222:225], 0
	v_mfma_f32_16x16x32_bf16 v[18:21], v[156:159], v[222:225], 0
	v_mfma_f32_16x16x32_bf16 v[62:65], v[152:155], v[184:187], v[62:65]
	v_mfma_f32_16x16x32_bf16 v[58:61], v[160:163], v[184:187], v[58:61]
	v_mfma_f32_16x16x32_bf16 v[54:57], v[152:155], v[192:195], v[54:57]
	v_mfma_f32_16x16x32_bf16 v[50:53], v[160:163], v[192:195], v[50:53]
	v_mfma_f32_16x16x32_bf16 v[38:41], v[152:155], v[218:221], v[38:41]
	v_mfma_f32_16x16x32_bf16 v[34:37], v[160:163], v[218:221], v[34:37]
	v_mfma_f32_16x16x32_bf16 v[22:25], v[152:155], v[226:229], v[22:25]
	v_mfma_f32_16x16x32_bf16 v[18:21], v[160:163], v[226:229], v[18:21]
	s_setprio 0
	s_setprio 1
	v_mfma_f32_16x16x32_bf16 v[46:49], v[164:167], v[180:183], 0
	v_mfma_f32_16x16x32_bf16 v[42:45], v[172:175], v[180:183], 0
	v_mfma_f32_16x16x32_bf16 v[30:33], v[164:167], v[188:191], 0
	v_mfma_f32_16x16x32_bf16 v[26:29], v[172:175], v[188:191], 0
	v_mfma_f32_16x16x32_bf16 v[14:17], v[164:167], v[214:217], 0
	v_mfma_f32_16x16x32_bf16 v[10:13], v[172:175], v[214:217], 0
	v_mfma_f32_16x16x32_bf16 v[6:9], v[164:167], v[222:225], 0
	v_mfma_f32_16x16x32_bf16 v[2:5], v[172:175], v[222:225], 0
	v_mfma_f32_16x16x32_bf16 v[46:49], v[168:171], v[184:187], v[46:49]
	v_mfma_f32_16x16x32_bf16 v[42:45], v[176:179], v[184:187], v[42:45]
	v_mfma_f32_16x16x32_bf16 v[30:33], v[168:171], v[192:195], v[30:33]
	v_mfma_f32_16x16x32_bf16 v[26:29], v[176:179], v[192:195], v[26:29]
	v_mfma_f32_16x16x32_bf16 v[14:17], v[168:171], v[218:221], v[14:17]
	v_mfma_f32_16x16x32_bf16 v[10:13], v[176:179], v[218:221], v[10:13]
	v_mfma_f32_16x16x32_bf16 v[6:9], v[168:171], v[226:229], v[6:9]
	v_mfma_f32_16x16x32_bf16 v[2:5], v[176:179], v[226:229], v[2:5]
	s_setprio 0
	s_barrier
	s_add_i32 s50, 0, 0x18000
	s_add_i32 s51, 0, 0x1c000
	v_add_u32_e32 v160, s50, v145
	v_add_u32_e32 v176, s51, v145
	ds_read_b128 v[148:151], v160
	ds_read_b128 v[152:155], v160 offset:1024
	ds_read_b128 v[156:159], v160 offset:2048
	ds_read_b128 v[160:163], v160 offset:3072
	ds_read_b128 v[164:167], v176
	ds_read_b128 v[168:171], v176 offset:1024
	ds_read_b128 v[172:175], v176 offset:2048
	ds_read_b128 v[176:179], v176 offset:3072
	s_add_u32 s30, s30, 0x40000
	s_addc_u32 s31, s31, 0
	s_add_u32 s98, s30, 0xfffc0080
	s_addc_u32 s99, s31, -1
	s_mov_b32 m0, s37
	ds_read_b128 v[180:183], v147 offset:32768
	ds_read_b128 v[184:187], v147 offset:33792
	ds_read_b128 v[188:191], v147 offset:34816
	ds_read_b128 v[192:195], v147 offset:35840
	ds_read_b128 v[214:217], v147 offset:36864
	ds_read_b128 v[218:221], v147 offset:37888
	ds_read_b128 v[222:225], v147 offset:38912
	ds_read_b128 v[226:229], v147 offset:39936
	global_load_lds_dwordx4 v134, s[30:31]
	s_mov_b32 m0, s40
	s_nop 0
	global_load_lds_dwordx4 v132, s[30:31]
	s_waitcnt vmcnt(8) lgkmcnt(0)
	s_barrier
	s_setprio 1
	v_mfma_f32_16x16x32_bf16 v[126:129], v[148:151], v[180:183], v[126:129]
	v_mfma_f32_16x16x32_bf16 v[122:125], v[156:159], v[180:183], v[122:125]
	v_mfma_f32_16x16x32_bf16 v[118:121], v[148:151], v[188:191], v[118:121]
	v_mfma_f32_16x16x32_bf16 v[114:117], v[156:159], v[188:191], v[114:117]
	v_mfma_f32_16x16x32_bf16 v[102:105], v[148:151], v[214:217], v[102:105]
	v_mfma_f32_16x16x32_bf16 v[98:101], v[156:159], v[214:217], v[98:101]
	v_mfma_f32_16x16x32_bf16 v[86:89], v[148:151], v[222:225], v[86:89]
	v_mfma_f32_16x16x32_bf16 v[82:85], v[156:159], v[222:225], v[82:85]
	v_mfma_f32_16x16x32_bf16 v[126:129], v[152:155], v[184:187], v[126:129]
	v_mfma_f32_16x16x32_bf16 v[122:125], v[160:163], v[184:187], v[122:125]
	v_mfma_f32_16x16x32_bf16 v[118:121], v[152:155], v[192:195], v[118:121]
	v_mfma_f32_16x16x32_bf16 v[114:117], v[160:163], v[192:195], v[114:117]
	v_mfma_f32_16x16x32_bf16 v[102:105], v[152:155], v[218:221], v[102:105]
	v_mfma_f32_16x16x32_bf16 v[98:101], v[160:163], v[218:221], v[98:101]
	v_mfma_f32_16x16x32_bf16 v[86:89], v[152:155], v[226:229], v[86:89]
	v_mfma_f32_16x16x32_bf16 v[82:85], v[160:163], v[226:229], v[82:85]
	s_setprio 0
	s_setprio 1
	v_mfma_f32_16x16x32_bf16 v[110:113], v[164:167], v[180:183], v[110:113]
	v_mfma_f32_16x16x32_bf16 v[106:109], v[172:175], v[180:183], v[106:109]
	v_mfma_f32_16x16x32_bf16 v[94:97], v[164:167], v[188:191], v[94:97]
	v_mfma_f32_16x16x32_bf16 v[90:93], v[172:175], v[188:191], v[90:93]
	v_mfma_f32_16x16x32_bf16 v[78:81], v[164:167], v[214:217], v[78:81]
	v_mfma_f32_16x16x32_bf16 v[74:77], v[172:175], v[214:217], v[74:77]
	v_mfma_f32_16x16x32_bf16 v[70:73], v[164:167], v[222:225], v[70:73]
	v_mfma_f32_16x16x32_bf16 v[66:69], v[172:175], v[222:225], v[66:69]
	v_mfma_f32_16x16x32_bf16 v[110:113], v[168:171], v[184:187], v[110:113]
	v_mfma_f32_16x16x32_bf16 v[106:109], v[176:179], v[184:187], v[106:109]
	v_mfma_f32_16x16x32_bf16 v[94:97], v[168:171], v[192:195], v[94:97]
	v_mfma_f32_16x16x32_bf16 v[90:93], v[176:179], v[192:195], v[90:93]
	v_mfma_f32_16x16x32_bf16 v[78:81], v[168:171], v[218:221], v[78:81]
	v_mfma_f32_16x16x32_bf16 v[74:77], v[176:179], v[218:221], v[74:77]
	v_mfma_f32_16x16x32_bf16 v[70:73], v[168:171], v[226:229], v[70:73]
	v_mfma_f32_16x16x32_bf16 v[66:69], v[176:179], v[226:229], v[66:69]
	s_setprio 0
	s_barrier
; #define PG8_STAGE(bufoff, gbase, voff) do { _Pragma("unroll") for (int _i = 0; _i < 2; ++_i) \
;         __builtin_amdgcn_global_load_lds((const unsigned*)((const char*)(gbase) + (voff)[_i]), (LAS unsigned*)(lds + (bufoff) + ldsw + _i * 8192), 16, 0, 0); } while (0)
; #define PG8_LDA(dst, b, h) do { _Pragma("unroll") for (int m = 0; m < 4; ++m) _Pragma("unroll") for (int k = 0; k < 2; ++k) dst[m][k] = *(const LAS f16x8*)(lds + PG8_SA(b, h) + aoff + m * 2048 + k * 1024); } while (0)
; #define PG8_MMA(ai, bj, At, Bt) do { __builtin_amdgcn_s_setprio(1); _Pragma("unroll") for (int m = 0; m < 4; ++m) _Pragma("unroll") for (int n = 0; n < 2; ++n) _Pragma("unroll") for (int k = 0; k < 2; ++k) \
;         acc[ai][bj][m][n] = mma16_<Epi::BF16>(Bt[n][k], At[m][k], acc[ai][bj][m][n]); __builtin_amdgcn_s_setprio(0); } while (0)
; #define PG8_WAIT_V(n) asm volatile("s_waitcnt vmcnt(" #n ")" ::: "memory")
; #define PG8_WAIT_L(n) asm volatile("s_waitcnt lgkmcnt(" #n ")" ::: "memory")
; #define PG8_BAR __builtin_amdgcn_s_barrier()
; #define PG8_SCHED __builtin_amdgcn_sched_barrier(0)
;     ...
;             PG8_LDA(At, 1, 1); PG8_STAGE(PG8_SB(1, 0), b3, voffB); PG8_STAGE(PG8_SB(1, 1), b3 + hB, voffB); PG8_STAGE(PG8_SA(1, 0), a3, voffA);
;             PG8_WAIT_V(8); PG8_WAIT_L(0); PG8_BAR; if (!cur.half) { PG8_MMA(1, 0, At, B0); PG8_MMA(1, 1, At, B1); } PG8_BAR; PG8_SCHED;
	s_add_i32 s30, s50, s34
	s_add_u32 s28, s28, 0x80
	s_addc_u32 s29, s29, 0
	s_mov_b32 m0, s30
	ds_read_b128 v[180:183], v147 offset:49152
	ds_read_b128 v[184:187], v147 offset:50176
	ds_read_b128 v[188:191], v147 offset:51200
	ds_read_b128 v[192:195], v147 offset:52224
	ds_read_b128 v[214:217], v147 offset:53248
	ds_read_b128 v[218:221], v147 offset:54272
	ds_read_b128 v[222:225], v147 offset:55296
	ds_read_b128 v[226:229], v147 offset:56320
	global_load_lds_dwordx4 v0, s[28:29]
	s_add_i32 m0, s30, 0x2000
	s_add_i32 s30, s51, s34
	global_load_lds_dwordx4 v130, s[28:29]
	s_add_u32 s28, s28, 0x40000
	s_addc_u32 s29, s29, 0
	s_mov_b32 m0, s30
	s_nop 0
	global_load_lds_dwordx4 v0, s[28:29]
	s_add_i32 m0, s30, 0x2000
	s_nop 0
	global_load_lds_dwordx4 v130, s[28:29]
	s_mov_b32 m0, s41
	s_nop 0
	global_load_lds_dwordx4 v134, s[98:99]
	s_mov_b32 m0, s42
	s_nop 0
	global_load_lds_dwordx4 v132, s[98:99]
	s_waitcnt vmcnt(8) lgkmcnt(0)
	s_barrier
	s_setprio 1
	v_mfma_f32_16x16x32_bf16 v[62:65], v[148:151], v[180:183], v[62:65]
	v_mfma_f32_16x16x32_bf16 v[58:61], v[156:159], v[180:183], v[58:61]
	v_mfma_f32_16x16x32_bf16 v[54:57], v[148:151], v[188:191], v[54:57]
	v_mfma_f32_16x16x32_bf16 v[50:53], v[156:159], v[188:191], v[50:53]
	v_mfma_f32_16x16x32_bf16 v[38:41], v[148:151], v[214:217], v[38:41]
	v_mfma_f32_16x16x32_bf16 v[34:37], v[156:159], v[214:217], v[34:37]
	v_mfma_f32_16x16x32_bf16 v[22:25], v[148:151], v[222:225], v[22:25]
	v_mfma_f32_16x16x32_bf16 v[18:21], v[156:159], v[222:225], v[18:21]
	v_mfma_f32_16x16x32_bf16 v[62:65], v[152:155], v[184:187], v[62:65]
	v_mfma_f32_16x16x32_bf16 v[58:61], v[160:163], v[184:187], v[58:61]
	v_mfma_f32_16x16x32_bf16 v[54:57], v[152:155], v[192:195], v[54:57]
	v_mfma_f32_16x16x32_bf16 v[50:53], v[160:163], v[192:195], v[50:53]
	v_mfma_f32_16x16x32_bf16 v[38:41], v[152:155], v[218:221], v[38:41]
	v_mfma_f32_16x16x32_bf16 v[34:37], v[160:163], v[218:221], v[34:37]
	v_mfma_f32_16x16x32_bf16 v[22:25], v[152:155], v[226:229], v[22:25]
	v_mfma_f32_16x16x32_bf16 v[18:21], v[160:163], v[226:229], v[18:21]
	s_setprio 0
	s_setprio 1
	v_mfma_f32_16x16x32_bf16 v[46:49], v[164:167], v[180:183], v[46:49]
	v_mfma_f32_16x16x32_bf16 v[42:45], v[172:175], v[180:183], v[42:45]
	v_mfma_f32_16x16x32_bf16 v[30:33], v[164:167], v[188:191], v[30:33]
	v_mfma_f32_16x16x32_bf16 v[26:29], v[172:175], v[188:191], v[26:29]
	v_mfma_f32_16x16x32_bf16 v[14:17], v[164:167], v[214:217], v[14:17]
	v_mfma_f32_16x16x32_bf16 v[10:13], v[172:175], v[214:217], v[10:13]
	v_mfma_f32_16x16x32_bf16 v[6:9], v[164:167], v[222:225], v[6:9]
	v_mfma_f32_16x16x32_bf16 v[2:5], v[172:175], v[222:225], v[2:5]
	v_mfma_f32_16x16x32_bf16 v[46:49], v[168:171], v[184:187], v[46:49]
	v_mfma_f32_16x16x32_bf16 v[42:45], v[176:179], v[184:187], v[42:45]
	v_mfma_f32_16x16x32_bf16 v[30:33], v[168:171], v[192:195], v[30:33]
	v_mfma_f32_16x16x32_bf16 v[26:29], v[176:179], v[192:195], v[26:29]
	v_mfma_f32_16x16x32_bf16 v[14:17], v[168:171], v[218:221], v[14:17]
	v_mfma_f32_16x16x32_bf16 v[10:13], v[176:179], v[218:221], v[10:13]
	v_mfma_f32_16x16x32_bf16 v[6:9], v[168:171], v[226:229], v[6:9]
	v_mfma_f32_16x16x32_bf16 v[2:5], v[176:179], v[226:229], v[2:5]
	s_setprio 0
	s_barrier
	s_add_i32 s49, s49, 2
	s_add_u32 s26, s26, 0x100
	s_addc_u32 s27, s27, 0
	s_add_u32 s47, s47, 0x100
	s_addc_u32 s48, s48, 0
	s_cmp_gt_u32 s49, 13
	.p2align	6

; #define PG8_STAGE(bufoff, gbase, voff) do { _Pragma("unroll") for (int _i = 0; _i < 2; ++_i) \
;         __builtin_amdgcn_global_load_lds((const unsigned*)((const char*)(gbase) + (voff)[_i]), (LAS unsigned*)(lds + (bufoff) + ldsw + _i * 8192), 16, 0, 0); } while (0)
; #define PG8_LDA(dst, b, h) do { _Pragma("unroll") for (int m = 0; m < 4; ++m) _Pragma("unroll") for (int k = 0; k < 2; ++k) dst[m][k] = *(const LAS f16x8*)(lds + PG8_SA(b, h) + aoff + m * 2048 + k * 1024); } while (0)
; #define PG8_LDB(dst, b, h) do { _Pragma("unroll") for (int n = 0; n < 2; ++n) _Pragma("unroll") for (int k = 0; k < 2; ++k) dst[n][k] = *(const LAS f16x8*)(lds + PG8_SB(b, h) + boff + n * 2048 + k * 1024); } while (0)
; #define PG8_WAIT_V(n) asm volatile("s_waitcnt vmcnt(" #n ")" ::: "memory")
; #define PG8_WAIT_L(n) asm volatile("s_waitcnt lgkmcnt(" #n ")" ::: "memory")
; #define PG8_BAR __builtin_amdgcn_s_barrier()
;     ...
;         for (int t = 0; t < nt; t += 2) {
;             const bool last = (t == nt - 2);
;             const char* a1 = cA + (size_t)(t + 1) * kstep;
;             const char* a2 = last ? nA : cA + (size_t)(t + 2) * kstep; const char* b2 = last ? nB : cB + (size_t)(t + 2) * kstep;
;             const char* a3 = a2 + kstep; const char* b3 = b2 + kstep;
;             if constexpr (SP2) {
;             PG8_LDB(B0, 0, 0); PG8_LDB(B1, 0, 1); PG8_SCHED; PG8_LDA(At, 0, 0); PG8_STAGE(PG8_SA(1, 1), a1 + hA, voffA);
;             PG8_WAIT_V(8); PG8_WAIT_L(0); PG8_BAR; PG8_MMA(0, 0, At, B0); PG8_MMA(0, 1, At, B1); PG8_BAR; PG8_SCHED;
;             PG8_LDA(At, 0, 1); PG8_STAGE(PG8_SB(0, 0), b2, voffB); PG8_STAGE(PG8_SB(0, 1), b2 + hB, voffB); PG8_STAGE(PG8_SA(0, 0), a2, voffA);
;             PG8_WAIT_V(8); PG8_WAIT_L(0); PG8_BAR; if (!cur.half) { PG8_MMA(1, 0, At, B0); PG8_MMA(1, 1, At, B1); } PG8_BAR; PG8_SCHED;
;             PG8_LDB(B0, 1, 0); PG8_LDB(B1, 1, 1); PG8_SCHED; PG8_LDA(At, 1, 0); PG8_STAGE(PG8_SA(0, 1), a2 + hA, voffA);
;             PG8_WAIT_V(8); PG8_WAIT_L(0); PG8_BAR; PG8_MMA(0, 0, At, B0); PG8_MMA(0, 1, At, B1); PG8_BAR; PG8_SCHED;
;             PG8_LDA(At, 1, 1); PG8_STAGE(PG8_SB(1, 0), b3, voffB); PG8_STAGE(PG8_SB(1, 1), b3 + hB, voffB); PG8_STAGE(PG8_SA(1, 0), a3, voffA);
;             PG8_WAIT_V(8); PG8_WAIT_L(0); PG8_BAR; if (!cur.half) { PG8_MMA(1, 0, At, B0); PG8_MMA(1, 1, At, B1); } PG8_BAR; PG8_SCHED;
.LBB0_757:
	s_barrier
	s_add_i32 s59, s59, 2
	s_add_u32 s23, s23, 0x100
	s_addc_u32 s58, s58, 0
	s_cmp_gt_u32 s59, 13
	s_cbranch_scc1 .LBB0_762
	.p2align	6

; #define PG8_STAGE(bufoff, gbase, voff) do { _Pragma("unroll") for (int _i = 0; _i < 2; ++_i) \
;         __builtin_amdgcn_global_load_lds((const unsigned*)((const char*)(gbase) + (voff)[_i]), (LAS unsigned*)(lds + (bufoff) + ldsw + _i * 8192), 16, 0, 0); } while (0)
; #define PG8_LDA(dst, b, h) do { _Pragma("unroll") for (int m = 0; m < 4; ++m) _Pragma("unroll") for (int k = 0; k < 2; ++k) dst[m][k] = *(const LAS f16x8*)(lds + PG8_SA(b, h) + aoff + m * 2048 + k * 1024); } while (0)
; #define PG8_LDB(dst, b, h) do { _Pragma("unroll") for (int n = 0; n < 2; ++n) _Pragma("unroll") for (int k = 0; k < 2; ++k) dst[n][k] = *(const LAS f16x8*)(lds + PG8_SB(b, h) + boff + n * 2048 + k * 1024); } while (0)
; #define PG8_WAIT_V(n) asm volatile("s_waitcnt vmcnt(" #n ")" ::: "memory")
; #define PG8_WAIT_L(n) asm volatile("s_waitcnt lgkmcnt(" #n ")" ::: "memory")
; #define PG8_BAR __builtin_amdgcn_s_barrier()
;     ...
;         for (int t = 0; t < nt; t += 2) {
;             const bool last = (t == nt - 2);
;             const char* a1 = cA + (size_t)(t + 1) * kstep;
;             const char* a2 = last ? nA : cA + (size_t)(t + 2) * kstep; const char* b2 = last ? nB : cB + (size_t)(t + 2) * kstep;
;             const char* a3 = a2 + kstep; const char* b3 = b2 + kstep;
;             if constexpr (SP2) {
;             PG8_LDB(B0, 0, 0); PG8_LDB(B1, 0, 1); PG8_SCHED; PG8_LDA(At, 0, 0); PG8_STAGE(PG8_SA(1, 1), a1 + hA, voffA);
;             PG8_WAIT_V(8); PG8_WAIT_L(0); PG8_BAR; PG8_MMA(0, 0, At, B0); PG8_MMA(0, 1, At, B1); PG8_BAR; PG8_SCHED;
;             PG8_LDA(At, 0, 1); PG8_STAGE(PG8_SB(0, 0), b2, voffB); PG8_STAGE(PG8_SB(0, 1), b2 + hB, voffB); PG8_STAGE(PG8_SA(0, 0), a2, voffA);
;             PG8_WAIT_V(8); PG8_WAIT_L(0); PG8_BAR; if (!cur.half) { PG8_MMA(1, 0, At, B0); PG8_MMA(1, 1, At, B1); } PG8_BAR; PG8_SCHED;
;             PG8_LDB(B0, 1, 0); PG8_LDB(B1, 1, 1); PG8_SCHED; PG8_LDA(At, 1, 0); PG8_STAGE(PG8_SA(0, 1), a2 + hA, voffA);
;             PG8_WAIT_V(8); PG8_WAIT_L(0); PG8_BAR; PG8_MMA(0, 0, At, B0); PG8_MMA(0, 1, At, B1); PG8_BAR; PG8_SCHED;
;             PG8_LDA(At, 1, 1); PG8_STAGE(PG8_SB(1, 0), b3, voffB); PG8_STAGE(PG8_SB(1, 1), b3 + hB, voffB); PG8_STAGE(PG8_SA(1, 0), a3, voffA);
;             PG8_WAIT_V(8); PG8_WAIT_L(0); PG8_BAR; if (!cur.half) { PG8_MMA(1, 0, At, B0); PG8_MMA(1, 1, At, B1); } PG8_BAR; PG8_SCHED;
.LBB0_797:
	s_barrier
	s_add_i32 s59, s59, 2
	s_add_u32 s49, s49, 0x100
	s_addc_u32 s58, s58, 0
	s_cmp_gt_u32 s59, 13
	s_cbranch_scc1 .LBB0_802
	.p2align	6

; #define PG8_STAGE(bufoff, gbase, voff) do { _Pragma("unroll") for (int _i = 0; _i < 2; ++_i) \
;         __builtin_amdgcn_global_load_lds((const unsigned*)((const char*)(gbase) + (voff)[_i]), (LAS unsigned*)(lds + (bufoff) + ldsw + _i * 8192), 16, 0, 0); } while (0)
; #define PG8_LDA(dst, b, h) do { _Pragma("unroll") for (int m = 0; m < 4; ++m) _Pragma("unroll") for (int k = 0; k < 2; ++k) dst[m][k] = *(const LAS f16x8*)(lds + PG8_SA(b, h) + aoff + m * 2048 + k * 1024); } while (0)
; #define PG8_LDB(dst, b, h) do { _Pragma("unroll") for (int n = 0; n < 2; ++n) _Pragma("unroll") for (int k = 0; k < 2; ++k) dst[n][k] = *(const LAS f16x8*)(lds + PG8_SB(b, h) + boff + n * 2048 + k * 1024); } while (0)
; #define PG8_WAIT_V(n) asm volatile("s_waitcnt vmcnt(" #n ")" ::: "memory")
; #define PG8_WAIT_L(n) asm volatile("s_waitcnt lgkmcnt(" #n ")" ::: "memory")
; #define PG8_BAR __builtin_amdgcn_s_barrier()
;     ...
;         for (int t = 0; t < nt; t += 2) {
;             const bool last = (t == nt - 2);
;             const char* a1 = cA + (size_t)(t + 1) * kstep;
;             const char* a2 = last ? nA : cA + (size_t)(t + 2) * kstep; const char* b2 = last ? nB : cB + (size_t)(t + 2) * kstep;
;             const char* a3 = a2 + kstep; const char* b3 = b2 + kstep;
;             if constexpr (SP2) {
;             PG8_LDB(B0, 0, 0); PG8_LDB(B1, 0, 1); PG8_SCHED; PG8_LDA(At, 0, 0); PG8_STAGE(PG8_SA(1, 1), a1 + hA, voffA);
;             PG8_WAIT_V(8); PG8_WAIT_L(0); PG8_BAR; PG8_MMA(0, 0, At, B0); PG8_MMA(0, 1, At, B1); PG8_BAR; PG8_SCHED;
;             PG8_LDA(At, 0, 1); PG8_STAGE(PG8_SB(0, 0), b2, voffB); PG8_STAGE(PG8_SB(0, 1), b2 + hB, voffB); PG8_STAGE(PG8_SA(0, 0), a2, voffA);
;             PG8_WAIT_V(8); PG8_WAIT_L(0); PG8_BAR; if (!cur.half) { PG8_MMA(1, 0, At, B0); PG8_MMA(1, 1, At, B1); } PG8_BAR; PG8_SCHED;
;             PG8_LDB(B0, 1, 0); PG8_LDB(B1, 1, 1); PG8_SCHED; PG8_LDA(At, 1, 0); PG8_STAGE(PG8_SA(0, 1), a2 + hA, voffA);
;             PG8_WAIT_V(8); PG8_WAIT_L(0); PG8_BAR; PG8_MMA(0, 0, At, B0); PG8_MMA(0, 1, At, B1); PG8_BAR; PG8_SCHED;
;             PG8_LDA(At, 1, 1); PG8_STAGE(PG8_SB(1, 0), b3, voffB); PG8_STAGE(PG8_SB(1, 1), b3 + hB, voffB); PG8_STAGE(PG8_SA(1, 0), a3, voffA);
;             PG8_WAIT_V(8); PG8_WAIT_L(0); PG8_BAR; if (!cur.half) { PG8_MMA(1, 0, At, B0); PG8_MMA(1, 1, At, B1); } PG8_BAR; PG8_SCHED;
.LBB0_885:
	s_barrier
	s_add_i32 s14, s14, 2
	s_add_u32 s36, s36, 0x100
	s_addc_u32 s37, s37, 0
	s_add_u32 s9, s9, 0x100
	s_addc_u32 s11, s11, 0
	s_cmp_gt_u32 s14, 13
	s_cbranch_scc1 .LBB0_890
	.p2align	6

; #define PG8_STAGE(bufoff, gbase, voff) do { _Pragma("unroll") for (int _i = 0; _i < 2; ++_i) \
;         __builtin_amdgcn_global_load_lds((const unsigned*)((const char*)(gbase) + (voff)[_i]), (LAS unsigned*)(lds + (bufoff) + ldsw + _i * 8192), 16, 0, 0); } while (0)
; #define PG8_LDA(dst, b, h) do { _Pragma("unroll") for (int m = 0; m < 4; ++m) _Pragma("unroll") for (int k = 0; k < 2; ++k) dst[m][k] = *(const LAS f16x8*)(lds + PG8_SA(b, h) + aoff + m * 2048 + k * 1024); } while (0)
; #define PG8_LDB(dst, b, h) do { _Pragma("unroll") for (int n = 0; n < 2; ++n) _Pragma("unroll") for (int k = 0; k < 2; ++k) dst[n][k] = *(const LAS f16x8*)(lds + PG8_SB(b, h) + boff + n * 2048 + k * 1024); } while (0)
; #define PG8_MMA(ai, bj, At, Bt) do { __builtin_amdgcn_s_setprio(1); _Pragma("unroll") for (int m = 0; m < 4; ++m) _Pragma("unroll") for (int n = 0; n < 2; ++n) _Pragma("unroll") for (int k = 0; k < 2; ++k) \
;         acc[ai][bj][m][n] = mma16_<Epi::BF16>(Bt[n][k], At[m][k], acc[ai][bj][m][n]); __builtin_amdgcn_s_setprio(0); } while (0)
; #define PG8_WAIT_V(n) asm volatile("s_waitcnt vmcnt(" #n ")" ::: "memory")
; #define PG8_WAIT_L(n) asm volatile("s_waitcnt lgkmcnt(" #n ")" ::: "memory")
; #define PG8_BAR __builtin_amdgcn_s_barrier()
;     ...
;         const char* nA = has_next ? (const char*)g.A + (size_t)nxt.pm * tA + (nxt.roff ? hA : (size_t)0) : cA; const char* nB = has_next ? (const char*)g.Bt + (size_t)nxt.pn * tB : cB;
;         for (int t = 0; t < nt; t += 2) {
;             const bool last = (t == nt - 2);
;             const char* a1 = cA + (size_t)(t + 1) * kstep;
;             const char* a2 = last ? nA : cA + (size_t)(t + 2) * kstep; const char* b2 = last ? nB : cB + (size_t)(t + 2) * kstep;
;             const char* a3 = a2 + kstep; const char* b3 = b2 + kstep;
;             if constexpr (SP2) {
;             PG8_LDB(B0, 0, 0); PG8_LDB(B1, 0, 1); PG8_SCHED; PG8_LDA(At, 0, 0); PG8_STAGE(PG8_SA(1, 1), a1 + hA, voffA);
;             PG8_WAIT_V(8); PG8_WAIT_L(0); PG8_BAR; PG8_MMA(0, 0, At, B0); PG8_MMA(0, 1, At, B1); PG8_BAR; PG8_SCHED;
;             PG8_LDA(At, 0, 1); PG8_STAGE(PG8_SB(0, 0), b2, voffB); PG8_STAGE(PG8_SB(0, 1), b2 + hB, voffB); PG8_STAGE(PG8_SA(0, 0), a2, voffA);
;             PG8_WAIT_V(8); PG8_WAIT_L(0); PG8_BAR; if (!cur.half) { PG8_MMA(1, 0, At, B0); PG8_MMA(1, 1, At, B1); } PG8_BAR; PG8_SCHED;
.LBB0_1017:
	s_ashr_i32 s21, s20, 31
	s_lshl_b64 s[2:3], s[20:21], 19
	s_add_u32 s22, s14, s2
	s_addc_u32 s23, s17, s3
	s_and_b64 s[2:3], s[38:39], exec
	s_cselect_b32 s2, s23, s31
	s_cselect_b32 s3, s22, s30
	s_ashr_i32 s19, s18, 31
	s_lshl_b64 s[24:25], s[18:19], 19
	s_add_u32 s24, s12, s24
	s_addc_u32 s25, s13, s25
	s_and_b64 s[36:37], s[38:39], exec
	s_cselect_b32 s19, s25, s35
	s_cselect_b32 s21, s24, s34
	s_add_u32 s30, s30, 0x40080
	s_addc_u32 s31, s31, 0
	s_add_u32 s51, s34, 0x100
	s_addc_u32 s52, s35, 0
	s_mov_b32 s53, -2
	s_add_u32 s34, s30, 0xfffc0080
	s_addc_u32 s35, s31, -1
	s_add_i32 s54, 0, 0x10000
	s_cmp_eq_u32 s53, 12
	s_cselect_b32 s37, s2, s35
	s_cselect_b32 s36, s3, s34
	s_cselect_b32 s35, s19, s52
	s_cselect_b32 s34, s21, s51
	s_add_i32 s56, 0, 0x14000
	v_add_u32_e32 v156, s54, v141
	v_add_u32_e32 v172, s56, v141
	ds_read_b128 v[144:147], v156
	ds_read_b128 v[148:151], v156 offset:1024
	ds_read_b128 v[152:155], v156 offset:2048
	ds_read_b128 v[156:159], v156 offset:3072
	ds_read_b128 v[160:163], v172
	ds_read_b128 v[164:167], v172 offset:1024
	ds_read_b128 v[168:171], v172 offset:2048
	ds_read_b128 v[172:175], v172 offset:3072
	s_add_i32 m0, s27, 0xc000
	ds_read_b128 v[176:179], v143
	ds_read_b128 v[180:183], v143 offset:1024
	ds_read_b128 v[184:187], v143 offset:2048
	ds_read_b128 v[188:191], v143 offset:3072
	ds_read_b128 v[192:195], v143 offset:4096
	ds_read_b128 v[200:203], v143 offset:5120
	ds_read_b128 v[214:217], v143 offset:6144
	ds_read_b128 v[218:221], v143 offset:7168
	global_load_lds_dwordx4 v136, s[30:31]
	s_add_i32 m0, s27, 0xe000
	s_nop 0
	global_load_lds_dwordx4 v138, s[30:31]
	s_waitcnt vmcnt(8) lgkmcnt(0)
	s_barrier
	s_setprio 1
	v_mfma_f32_16x16x32_bf16 v[126:129], v[144:147], v[176:179], 0
	v_mfma_f32_16x16x32_bf16 v[118:121], v[152:155], v[176:179], 0
	v_mfma_f32_16x16x32_bf16 v[110:113], v[144:147], v[184:187], 0
	v_mfma_f32_16x16x32_bf16 v[102:105], v[152:155], v[184:187], 0
	v_mfma_f32_16x16x32_bf16 v[94:97], v[144:147], v[192:195], 0
	v_mfma_f32_16x16x32_bf16 v[86:89], v[152:155], v[192:195], 0
	v_mfma_f32_16x16x32_bf16 v[78:81], v[144:147], v[214:217], 0
	v_mfma_f32_16x16x32_bf16 v[70:73], v[152:155], v[214:217], 0
	v_mfma_f32_16x16x32_bf16 v[126:129], v[148:151], v[180:183], v[126:129]
	v_mfma_f32_16x16x32_bf16 v[118:121], v[156:159], v[180:183], v[118:121]
	v_mfma_f32_16x16x32_bf16 v[110:113], v[148:151], v[188:191], v[110:113]
	v_mfma_f32_16x16x32_bf16 v[102:105], v[156:159], v[188:191], v[102:105]
	v_mfma_f32_16x16x32_bf16 v[94:97], v[148:151], v[200:203], v[94:97]
	v_mfma_f32_16x16x32_bf16 v[86:89], v[156:159], v[200:203], v[86:89]
	v_mfma_f32_16x16x32_bf16 v[78:81], v[148:151], v[218:221], v[78:81]
	v_mfma_f32_16x16x32_bf16 v[70:73], v[156:159], v[218:221], v[70:73]
	s_setprio 0
	s_setprio 1
	v_mfma_f32_16x16x32_bf16 v[122:125], v[160:163], v[176:179], 0
	v_mfma_f32_16x16x32_bf16 v[114:117], v[168:171], v[176:179], 0
	v_mfma_f32_16x16x32_bf16 v[106:109], v[160:163], v[184:187], 0
	v_mfma_f32_16x16x32_bf16 v[98:101], v[168:171], v[184:187], 0
	v_mfma_f32_16x16x32_bf16 v[90:93], v[160:163], v[192:195], 0
	v_mfma_f32_16x16x32_bf16 v[82:85], v[168:171], v[192:195], 0
	v_mfma_f32_16x16x32_bf16 v[74:77], v[160:163], v[214:217], 0
	v_mfma_f32_16x16x32_bf16 v[66:69], v[168:171], v[214:217], 0
	v_mfma_f32_16x16x32_bf16 v[122:125], v[164:167], v[180:183], v[122:125]
	v_mfma_f32_16x16x32_bf16 v[114:117], v[172:175], v[180:183], v[114:117]
	v_mfma_f32_16x16x32_bf16 v[106:109], v[164:167], v[188:191], v[106:109]
	v_mfma_f32_16x16x32_bf16 v[98:101], v[172:175], v[188:191], v[98:101]
	v_mfma_f32_16x16x32_bf16 v[90:93], v[164:167], v[200:203], v[90:93]
	v_mfma_f32_16x16x32_bf16 v[82:85], v[172:175], v[200:203], v[82:85]
	v_mfma_f32_16x16x32_bf16 v[74:77], v[164:167], v[218:221], v[74:77]
	v_mfma_f32_16x16x32_bf16 v[66:69], v[172:175], v[218:221], v[66:69]
	s_setprio 0
	s_barrier
	s_add_i32 s54, s54, s40
	s_mov_b32 m0, s54
	ds_read_b128 v[176:179], v143 offset:16384
	ds_read_b128 v[180:183], v143 offset:17408
	ds_read_b128 v[184:187], v143 offset:18432
	ds_read_b128 v[188:191], v143 offset:19456
	ds_read_b128 v[192:195], v143 offset:20480
	ds_read_b128 v[200:203], v143 offset:21504
	ds_read_b128 v[214:217], v143 offset:22528
	ds_read_b128 v[218:221], v143 offset:23552
	global_load_lds_dwordx4 v0, s[34:35]
	s_add_i32 m0, s54, 0x2000
	s_add_u32 s54, s34, 0x40000
	s_addc_u32 s55, s35, 0
	s_add_i32 s56, s56, s40
	global_load_lds_dwordx4 v130, s[34:35]
	s_mov_b32 m0, s56
	s_nop 0
	global_load_lds_dwordx4 v0, s[54:55]
	s_add_i32 m0, s56, 0x2000
	s_nop 0
	global_load_lds_dwordx4 v130, s[54:55]
	s_mov_b32 m0, s27
	s_nop 0
	global_load_lds_dwordx4 v134, s[36:37]
	s_mov_b32 m0, s29
	s_nop 0
	global_load_lds_dwordx4 v132, s[36:37]
	s_waitcnt vmcnt(8) lgkmcnt(0)
	s_barrier
; #define PG8_STAGE(bufoff, gbase, voff) do { _Pragma("unroll") for (int _i = 0; _i < 2; ++_i) \
;         __builtin_amdgcn_global_load_lds((const unsigned*)((const char*)(gbase) + (voff)[_i]), (LAS unsigned*)(lds + (bufoff) + ldsw + _i * 8192), 16, 0, 0); } while (0)
; #define PG8_LDA(dst, b, h) do { _Pragma("unroll") for (int m = 0; m < 4; ++m) _Pragma("unroll") for (int k = 0; k < 2; ++k) dst[m][k] = *(const LAS f16x8*)(lds + PG8_SA(b, h) + aoff + m * 2048 + k * 1024); } while (0)
; #define PG8_LDB(dst, b, h) do { _Pragma("unroll") for (int n = 0; n < 2; ++n) _Pragma("unroll") for (int k = 0; k < 2; ++k) dst[n][k] = *(const LAS f16x8*)(lds + PG8_SB(b, h) + boff + n * 2048 + k * 1024); } while (0)
; #define PG8_MMA(ai, bj, At, Bt) do { __builtin_amdgcn_s_setprio(1); _Pragma("unroll") for (int m = 0; m < 4; ++m) _Pragma("unroll") for (int n = 0; n < 2; ++n) _Pragma("unroll") for (int k = 0; k < 2; ++k) \
;         acc[ai][bj][m][n] = mma16_<Epi::BF16>(Bt[n][k], At[m][k], acc[ai][bj][m][n]); __builtin_amdgcn_s_setprio(0); } while (0)
; #define PG8_WAIT_V(n) asm volatile("s_waitcnt vmcnt(" #n ")" ::: "memory")
; #define PG8_WAIT_L(n) asm volatile("s_waitcnt lgkmcnt(" #n ")" ::: "memory")
; #define PG8_BAR __builtin_amdgcn_s_barrier()
; #define PG8_SCHED __builtin_amdgcn_sched_barrier(0)
;     ...
;             PG8_WAIT_V(8); PG8_WAIT_L(0); PG8_BAR; if (!cur.half) { PG8_MMA(1, 0, At, B0); PG8_MMA(1, 1, At, B1); } PG8_BAR; PG8_SCHED;
;             PG8_LDB(B0, 1, 0); PG8_LDB(B1, 1, 1); PG8_SCHED; PG8_LDA(At, 1, 0); PG8_STAGE(PG8_SA(0, 1), a2 + hA, voffA);
;             PG8_WAIT_V(8); PG8_WAIT_L(0); PG8_BAR; PG8_MMA(0, 0, At, B0); PG8_MMA(0, 1, At, B1); PG8_BAR; PG8_SCHED;
	s_setprio 1
	v_mfma_f32_16x16x32_bf16 v[62:65], v[144:147], v[176:179], 0
	v_mfma_f32_16x16x32_bf16 v[54:57], v[152:155], v[176:179], 0
	v_mfma_f32_16x16x32_bf16 v[46:49], v[144:147], v[184:187], 0
	v_mfma_f32_16x16x32_bf16 v[38:41], v[152:155], v[184:187], 0
	v_mfma_f32_16x16x32_bf16 v[30:33], v[144:147], v[192:195], 0
	v_mfma_f32_16x16x32_bf16 v[22:25], v[152:155], v[192:195], 0
	v_mfma_f32_16x16x32_bf16 v[14:17], v[144:147], v[214:217], 0
	v_mfma_f32_16x16x32_bf16 v[6:9], v[152:155], v[214:217], 0
	v_mfma_f32_16x16x32_bf16 v[62:65], v[148:151], v[180:183], v[62:65]
	v_mfma_f32_16x16x32_bf16 v[54:57], v[156:159], v[180:183], v[54:57]
	v_mfma_f32_16x16x32_bf16 v[46:49], v[148:151], v[188:191], v[46:49]
	v_mfma_f32_16x16x32_bf16 v[38:41], v[156:159], v[188:191], v[38:41]
	v_mfma_f32_16x16x32_bf16 v[30:33], v[148:151], v[200:203], v[30:33]
	v_mfma_f32_16x16x32_bf16 v[22:25], v[156:159], v[200:203], v[22:25]
	v_mfma_f32_16x16x32_bf16 v[14:17], v[148:151], v[218:221], v[14:17]
	v_mfma_f32_16x16x32_bf16 v[6:9], v[156:159], v[218:221], v[6:9]
	s_setprio 0
	s_setprio 1
	v_mfma_f32_16x16x32_bf16 v[58:61], v[160:163], v[176:179], 0
	v_mfma_f32_16x16x32_bf16 v[50:53], v[168:171], v[176:179], 0
	v_mfma_f32_16x16x32_bf16 v[42:45], v[160:163], v[184:187], 0
	v_mfma_f32_16x16x32_bf16 v[34:37], v[168:171], v[184:187], 0
	v_mfma_f32_16x16x32_bf16 v[26:29], v[160:163], v[192:195], 0
	v_mfma_f32_16x16x32_bf16 v[18:21], v[168:171], v[192:195], 0
	v_mfma_f32_16x16x32_bf16 v[10:13], v[160:163], v[214:217], 0
	v_mfma_f32_16x16x32_bf16 v[2:5], v[168:171], v[214:217], 0
	v_mfma_f32_16x16x32_bf16 v[58:61], v[164:167], v[180:183], v[58:61]
	v_mfma_f32_16x16x32_bf16 v[50:53], v[172:175], v[180:183], v[50:53]
	v_mfma_f32_16x16x32_bf16 v[42:45], v[164:167], v[188:191], v[42:45]
	v_mfma_f32_16x16x32_bf16 v[34:37], v[172:175], v[188:191], v[34:37]
	v_mfma_f32_16x16x32_bf16 v[26:29], v[164:167], v[200:203], v[26:29]
	v_mfma_f32_16x16x32_bf16 v[18:21], v[172:175], v[200:203], v[18:21]
	v_mfma_f32_16x16x32_bf16 v[10:13], v[164:167], v[218:221], v[10:13]
	v_mfma_f32_16x16x32_bf16 v[2:5], v[172:175], v[218:221], v[2:5]
	s_setprio 0
	s_barrier
	s_add_i32 s54, 0, 0x18000
	s_add_i32 s55, 0, 0x1c000
	v_add_u32_e32 v156, s54, v141
	v_add_u32_e32 v172, s55, v141
	ds_read_b128 v[144:147], v156
	ds_read_b128 v[148:151], v156 offset:1024
	ds_read_b128 v[152:155], v156 offset:2048
	ds_read_b128 v[156:159], v156 offset:3072
	ds_read_b128 v[160:163], v172
	ds_read_b128 v[164:167], v172 offset:1024
	ds_read_b128 v[168:171], v172 offset:2048
	ds_read_b128 v[172:175], v172 offset:3072
	s_add_u32 s36, s36, 0x40000
	s_addc_u32 s37, s37, 0
	s_add_u32 s98, s36, 0xfffc0080
	s_addc_u32 s99, s37, -1
	s_mov_b32 m0, s43
	ds_read_b128 v[176:179], v143 offset:32768
	ds_read_b128 v[180:183], v143 offset:33792
	ds_read_b128 v[184:187], v143 offset:34816
	ds_read_b128 v[188:191], v143 offset:35840
	ds_read_b128 v[192:195], v143 offset:36864
	ds_read_b128 v[200:203], v143 offset:37888
	ds_read_b128 v[214:217], v143 offset:38912
	ds_read_b128 v[218:221], v143 offset:39936
	global_load_lds_dwordx4 v134, s[36:37]
	s_mov_b32 m0, s44
	s_nop 0
	global_load_lds_dwordx4 v132, s[36:37]
	s_waitcnt vmcnt(8) lgkmcnt(0)
	s_barrier
	s_setprio 1
	v_mfma_f32_16x16x32_bf16 v[126:129], v[144:147], v[176:179], v[126:129]
	v_mfma_f32_16x16x32_bf16 v[118:121], v[152:155], v[176:179], v[118:121]
	v_mfma_f32_16x16x32_bf16 v[110:113], v[144:147], v[184:187], v[110:113]
	v_mfma_f32_16x16x32_bf16 v[102:105], v[152:155], v[184:187], v[102:105]
	v_mfma_f32_16x16x32_bf16 v[94:97], v[144:147], v[192:195], v[94:97]
	v_mfma_f32_16x16x32_bf16 v[86:89], v[152:155], v[192:195], v[86:89]
	v_mfma_f32_16x16x32_bf16 v[78:81], v[144:147], v[214:217], v[78:81]
	v_mfma_f32_16x16x32_bf16 v[70:73], v[152:155], v[214:217], v[70:73]
	v_mfma_f32_16x16x32_bf16 v[126:129], v[148:151], v[180:183], v[126:129]
	v_mfma_f32_16x16x32_bf16 v[118:121], v[156:159], v[180:183], v[118:121]
	v_mfma_f32_16x16x32_bf16 v[110:113], v[148:151], v[188:191], v[110:113]
	v_mfma_f32_16x16x32_bf16 v[102:105], v[156:159], v[188:191], v[102:105]
	v_mfma_f32_16x16x32_bf16 v[94:97], v[148:151], v[200:203], v[94:97]
	v_mfma_f32_16x16x32_bf16 v[86:89], v[156:159], v[200:203], v[86:89]
	v_mfma_f32_16x16x32_bf16 v[78:81], v[148:151], v[218:221], v[78:81]
	v_mfma_f32_16x16x32_bf16 v[70:73], v[156:159], v[218:221], v[70:73]
	s_setprio 0
	s_setprio 1
	v_mfma_f32_16x16x32_bf16 v[122:125], v[160:163], v[176:179], v[122:125]
	v_mfma_f32_16x16x32_bf16 v[114:117], v[168:171], v[176:179], v[114:117]
	v_mfma_f32_16x16x32_bf16 v[106:109], v[160:163], v[184:187], v[106:109]
	v_mfma_f32_16x16x32_bf16 v[98:101], v[168:171], v[184:187], v[98:101]
	v_mfma_f32_16x16x32_bf16 v[90:93], v[160:163], v[192:195], v[90:93]
	v_mfma_f32_16x16x32_bf16 v[82:85], v[168:171], v[192:195], v[82:85]
	v_mfma_f32_16x16x32_bf16 v[74:77], v[160:163], v[214:217], v[74:77]
	v_mfma_f32_16x16x32_bf16 v[66:69], v[168:171], v[214:217], v[66:69]
	v_mfma_f32_16x16x32_bf16 v[122:125], v[164:167], v[180:183], v[122:125]
	v_mfma_f32_16x16x32_bf16 v[114:117], v[172:175], v[180:183], v[114:117]
	v_mfma_f32_16x16x32_bf16 v[106:109], v[164:167], v[188:191], v[106:109]
	v_mfma_f32_16x16x32_bf16 v[98:101], v[172:175], v[188:191], v[98:101]
	v_mfma_f32_16x16x32_bf16 v[90:93], v[164:167], v[200:203], v[90:93]
	v_mfma_f32_16x16x32_bf16 v[82:85], v[172:175], v[200:203], v[82:85]
	v_mfma_f32_16x16x32_bf16 v[74:77], v[164:167], v[218:221], v[74:77]
	v_mfma_f32_16x16x32_bf16 v[66:69], v[172:175], v[218:221], v[66:69]
	s_setprio 0
	s_barrier
; #define PG8_STAGE(bufoff, gbase, voff) do { _Pragma("unroll") for (int _i = 0; _i < 2; ++_i) \
;         __builtin_amdgcn_global_load_lds((const unsigned*)((const char*)(gbase) + (voff)[_i]), (LAS unsigned*)(lds + (bufoff) + ldsw + _i * 8192), 16, 0, 0); } while (0)
; #define PG8_LDA(dst, b, h) do { _Pragma("unroll") for (int m = 0; m < 4; ++m) _Pragma("unroll") for (int k = 0; k < 2; ++k) dst[m][k] = *(const LAS f16x8*)(lds + PG8_SA(b, h) + aoff + m * 2048 + k * 1024); } while (0)
; #define PG8_MMA(ai, bj, At, Bt) do { __builtin_amdgcn_s_setprio(1); _Pragma("unroll") for (int m = 0; m < 4; ++m) _Pragma("unroll") for (int n = 0; n < 2; ++n) _Pragma("unroll") for (int k = 0; k < 2; ++k) \
;         acc[ai][bj][m][n] = mma16_<Epi::BF16>(Bt[n][k], At[m][k], acc[ai][bj][m][n]); __builtin_amdgcn_s_setprio(0); } while (0)
; #define PG8_WAIT_V(n) asm volatile("s_waitcnt vmcnt(" #n ")" ::: "memory")
; #define PG8_WAIT_L(n) asm volatile("s_waitcnt lgkmcnt(" #n ")" ::: "memory")
; #define PG8_BAR __builtin_amdgcn_s_barrier()
; #define PG8_SCHED __builtin_amdgcn_sched_barrier(0)
;     ...
;             PG8_LDA(At, 1, 1); PG8_STAGE(PG8_SB(1, 0), b3, voffB); PG8_STAGE(PG8_SB(1, 1), b3 + hB, voffB); PG8_STAGE(PG8_SA(1, 0), a3, voffA);
;             PG8_WAIT_V(8); PG8_WAIT_L(0); PG8_BAR; if (!cur.half) { PG8_MMA(1, 0, At, B0); PG8_MMA(1, 1, At, B1); } PG8_BAR; PG8_SCHED;
	s_add_i32 s36, s54, s40
	s_add_u32 s34, s34, 0x80
	s_addc_u32 s35, s35, 0
	s_mov_b32 m0, s36
	ds_read_b128 v[176:179], v143 offset:49152
	ds_read_b128 v[180:183], v143 offset:50176
	ds_read_b128 v[184:187], v143 offset:51200
	ds_read_b128 v[188:191], v143 offset:52224
	ds_read_b128 v[192:195], v143 offset:53248
	ds_read_b128 v[200:203], v143 offset:54272
	ds_read_b128 v[214:217], v143 offset:55296
	ds_read_b128 v[218:221], v143 offset:56320
	global_load_lds_dwordx4 v0, s[34:35]
	s_add_i32 m0, s36, 0x2000
	s_add_i32 s36, s55, s40
	global_load_lds_dwordx4 v130, s[34:35]
	s_add_u32 s34, s34, 0x40000
	s_addc_u32 s35, s35, 0
	s_mov_b32 m0, s36
	s_nop 0
	global_load_lds_dwordx4 v0, s[34:35]
	s_add_i32 m0, s36, 0x2000
	s_nop 0
	global_load_lds_dwordx4 v130, s[34:35]
	s_mov_b32 m0, s45
	s_nop 0
	global_load_lds_dwordx4 v134, s[98:99]
	s_mov_b32 m0, s47
	s_nop 0
	global_load_lds_dwordx4 v132, s[98:99]
	s_waitcnt vmcnt(8) lgkmcnt(0)
	s_barrier
	s_setprio 1
	v_mfma_f32_16x16x32_bf16 v[62:65], v[144:147], v[176:179], v[62:65]
	v_mfma_f32_16x16x32_bf16 v[54:57], v[152:155], v[176:179], v[54:57]
	v_mfma_f32_16x16x32_bf16 v[46:49], v[144:147], v[184:187], v[46:49]
	v_mfma_f32_16x16x32_bf16 v[38:41], v[152:155], v[184:187], v[38:41]
	v_mfma_f32_16x16x32_bf16 v[30:33], v[144:147], v[192:195], v[30:33]
	v_mfma_f32_16x16x32_bf16 v[22:25], v[152:155], v[192:195], v[22:25]
	v_mfma_f32_16x16x32_bf16 v[14:17], v[144:147], v[214:217], v[14:17]
	v_mfma_f32_16x16x32_bf16 v[6:9], v[152:155], v[214:217], v[6:9]
	v_mfma_f32_16x16x32_bf16 v[62:65], v[148:151], v[180:183], v[62:65]
	v_mfma_f32_16x16x32_bf16 v[54:57], v[156:159], v[180:183], v[54:57]
	v_mfma_f32_16x16x32_bf16 v[46:49], v[148:151], v[188:191], v[46:49]
	v_mfma_f32_16x16x32_bf16 v[38:41], v[156:159], v[188:191], v[38:41]
	v_mfma_f32_16x16x32_bf16 v[30:33], v[148:151], v[200:203], v[30:33]
	v_mfma_f32_16x16x32_bf16 v[22:25], v[156:159], v[200:203], v[22:25]
	v_mfma_f32_16x16x32_bf16 v[14:17], v[148:151], v[218:221], v[14:17]
	v_mfma_f32_16x16x32_bf16 v[6:9], v[156:159], v[218:221], v[6:9]
	s_setprio 0
	s_setprio 1
	v_mfma_f32_16x16x32_bf16 v[58:61], v[160:163], v[176:179], v[58:61]
	v_mfma_f32_16x16x32_bf16 v[50:53], v[168:171], v[176:179], v[50:53]
	v_mfma_f32_16x16x32_bf16 v[42:45], v[160:163], v[184:187], v[42:45]
	v_mfma_f32_16x16x32_bf16 v[34:37], v[168:171], v[184:187], v[34:37]
	v_mfma_f32_16x16x32_bf16 v[26:29], v[160:163], v[192:195], v[26:29]
	v_mfma_f32_16x16x32_bf16 v[18:21], v[168:171], v[192:195], v[18:21]
	v_mfma_f32_16x16x32_bf16 v[10:13], v[160:163], v[214:217], v[10:13]
	v_mfma_f32_16x16x32_bf16 v[2:5], v[168:171], v[214:217], v[2:5]
	v_mfma_f32_16x16x32_bf16 v[58:61], v[164:167], v[180:183], v[58:61]
	v_mfma_f32_16x16x32_bf16 v[50:53], v[172:175], v[180:183], v[50:53]
	v_mfma_f32_16x16x32_bf16 v[42:45], v[164:167], v[188:191], v[42:45]
	v_mfma_f32_16x16x32_bf16 v[34:37], v[172:175], v[188:191], v[34:37]
	v_mfma_f32_16x16x32_bf16 v[26:29], v[164:167], v[200:203], v[26:29]
	v_mfma_f32_16x16x32_bf16 v[18:21], v[172:175], v[200:203], v[18:21]
	v_mfma_f32_16x16x32_bf16 v[10:13], v[164:167], v[218:221], v[10:13]
	v_mfma_f32_16x16x32_bf16 v[2:5], v[172:175], v[218:221], v[2:5]
	s_setprio 0
	s_barrier
	s_add_i32 s53, s53, 2
	s_add_u32 s30, s30, 0x100
	s_addc_u32 s31, s31, 0
	s_add_u32 s51, s51, 0x100
	s_addc_u32 s52, s52, 0
	s_cmp_gt_u32 s53, 13
	.p2align	6
